# peer_down rewritten by hand: 8 column-slice sweeps of the fp8 down table (L2-resident 2 MiB slices), gathers of 8 rows x 128 B, pipelined loads
# speedup vs baseline: 1.0531x; 1.0470x over previous
; DI float bflo(unsigned u) { return __uint_as_float(u << 16); }
; DI float bfhi(unsigned u) { return __uint_as_float(u & 0xffff0000u); }
; DI void phase_peer_down(const Params& p) {
;   const char* exd = p.ws + OFF_EXD;
;   const float* esc = (const float*)(p.ws + OFF_ESC);
;   const u16* hb = (const u16*)(p.ws + OFF_HB);
;   const int* eidx = (const int*)(p.ws + OFF_EIDX);
;   const float* gate = (const float*)(p.ws + OFF_GATE);
;   float* coefw = (float*)(p.ws + OFF_COEF);
;   const int lane = threadIdx.x & 63;
;   const int gw = (blockIdx.x * blockDim.x + threadIdx.x) >> 6;
;   const int nw = (gridDim.x * blockDim.x) >> 6;
; #pragma unroll 1
;   for (int tok = gw; tok < T_; tok += nw) {
;     float x[16];
;     {
;       const u16* xr = hb + (size_t)tok * 1024 + lane * 16;
;       u32x4 a = *reinterpret_cast<const u32x4*>(xr);
;       u32x4 c = *reinterpret_cast<const u32x4*>(xr + 8);
; #pragma unroll
;       for (int w = 0; w < 4; ++w) { x[2 * w] = bflo(a[w]); x[2 * w + 1] = bfhi(a[w]); x[8 + 2 * w] = bflo(c[w]); x[8 + 2 * w + 1] = bfhi(c[w]); }
;     }
; #pragma unroll 1
;     for (int half = 0; half < 2; ++half) {
;       const size_t slot = (size_t)tok * 128 + half * 64 + lane;
;       const int ev = eidx[slot];
;       const float gv = gate[slot];
;       float racc = 0.f, gacc = 0.f;
; #pragma unroll 1
;       for (int bi = 0; bi < 8; ++bi) {
;         u32x4 dr[8];
; #pragma unroll
;         for (int k = 0; k < 8; ++k) {
;           const int er = __builtin_amdgcn_readlane(ev, bi * 8 + k);
;           dr[k] = *reinterpret_cast<const u32x4*>(exd + (size_t)er * 1024 + lane * 16);
.LBB0_1022:
	s_or_b64 exec, exec, s[0:1]
	s_add_u32 s0, s96, 0x2000000
	s_mov_b32 s2, 0x200000
	s_addc_u32 s1, s97, 0
	s_lshr_b32 s33, s20, 6
	v_cmp_gt_u32_e64 s[2:3], s2, v140
	v_lshrrev_b32_e32 v64, 6, v140
	s_waitcnt lgkmcnt(0)
	s_barrier
	s_and_saveexec_b64 s[10:11], s[2:3]
	s_cbranch_execz .LBB0_1033
	s_mov_b32 s4, s96
	s_mov_b32 s5, s97
	s_add_u32 s6, s96, 0x4000000
	s_addc_u32 s7, s97, 0
	s_add_u32 s8, s96, 0x12800000
	s_addc_u32 s9, s97, 0
	s_add_u32 s12, s96, 0xa500000
	s_addc_u32 s13, s97, 0
	s_add_u32 s14, s96, 0x1000000
	s_addc_u32 s15, s97, 0
	s_add_u32 s16, s96, 0x2000000
	s_addc_u32 s17, s97, 0
	s_add_u32 s34, s96, 0xa510000
	s_addc_u32 s35, s97, 0
	v_and_b32_e32 v0, 63, v166
	v_lshrrev_b32_e32 v1, 3, v0
	v_lshlrev_b32_e32 v1, 2, v1
	v_and_b32_e32 v2, 7, v0
	v_cmp_eq_u32_e32 vcc, 0, v2
	s_nop 1
	v_cndmask_b32_e64 v12, 0, 1.0, vcc
	v_cmp_eq_u32_e32 vcc, 1, v2
	s_nop 1
	v_cndmask_b32_e64 v13, 0, 1.0, vcc
	v_cmp_eq_u32_e32 vcc, 2, v2
	s_nop 1
	v_cndmask_b32_e64 v14, 0, 1.0, vcc
	v_cmp_eq_u32_e32 vcc, 3, v2
	s_nop 1
	v_cndmask_b32_e64 v15, 0, 1.0, vcc
	v_cmp_eq_u32_e32 vcc, 4, v2
	s_nop 1
	v_cndmask_b32_e64 v16, 0, 1.0, vcc
	v_cmp_eq_u32_e32 vcc, 5, v2
	s_nop 1
	v_cndmask_b32_e64 v17, 0, 1.0, vcc
	v_cmp_eq_u32_e32 vcc, 6, v2
	s_nop 1
	v_cndmask_b32_e64 v18, 0, 1.0, vcc
	v_cmp_eq_u32_e32 vcc, 7, v2
	s_nop 1
	v_cndmask_b32_e64 v19, 0, 1.0, vcc
	v_lshlrev_b32_e32 v3, 5, v2
	v_lshlrev_b32_e32 v2, 4, v2
	v_lshrrev_b32_e32 v4, 6, v166
	v_lshlrev_b32_e32 v4, 13, v4
	v_lshl_add_u32 v4, v0, 3, v4
	v_mov_b32_e32 v98, 0
	v_mov_b32_e32 v99, 0
	ds_write_b64 v4, v[98:99] offset:0
	ds_write_b64 v4, v[98:99] offset:512
	ds_write_b64 v4, v[98:99] offset:1024
	ds_write_b64 v4, v[98:99] offset:1536
	ds_write_b64 v4, v[98:99] offset:2048
	ds_write_b64 v4, v[98:99] offset:2560
	ds_write_b64 v4, v[98:99] offset:3072
	ds_write_b64 v4, v[98:99] offset:3584
	ds_write_b64 v4, v[98:99] offset:4096
	ds_write_b64 v4, v[98:99] offset:4608
	ds_write_b64 v4, v[98:99] offset:5120
	ds_write_b64 v4, v[98:99] offset:5632
	ds_write_b64 v4, v[98:99] offset:6144
	ds_write_b64 v4, v[98:99] offset:6656
	ds_write_b64 v4, v[98:99] offset:7168
	ds_write_b64 v4, v[98:99] offset:7680
	v_lshl_add_u32 v7, v64, 11, v3
	global_load_dwordx4 v[20:23], v7, s[8:9]
	global_load_dwordx4 v[24:27], v7, s[8:9] offset:16
	v_lshl_add_u32 v9, v64, 9, v1
	global_load_dword v100, v9, s[4:5] offset:0
	global_load_dword v101, v9, s[4:5] offset:32
	global_load_dword v102, v9, s[4:5] offset:64
	global_load_dword v103, v9, s[4:5] offset:96
	global_load_dword v104, v9, s[4:5] offset:128
	global_load_dword v105, v9, s[4:5] offset:160
	global_load_dword v106, v9, s[4:5] offset:192
	global_load_dword v107, v9, s[4:5] offset:224
	global_load_dword v108, v9, s[4:5] offset:256
	global_load_dword v109, v9, s[4:5] offset:288
	global_load_dword v110, v9, s[4:5] offset:320
	global_load_dword v111, v9, s[4:5] offset:352
	global_load_dword v112, v9, s[4:5] offset:384
	global_load_dword v113, v9, s[4:5] offset:416
	global_load_dword v114, v9, s[4:5] offset:448
	global_load_dword v115, v9, s[4:5] offset:480
	v_add_u32_e32 v5, 0x800, v64
	v_lshl_add_u32 v9, v5, 9, v1
	global_load_dword v232, v9, s[4:5] offset:0
	global_load_dword v233, v9, s[4:5] offset:32
	global_load_dword v234, v9, s[4:5] offset:64
	global_load_dword v235, v9, s[4:5] offset:96
	global_load_dword v236, v9, s[4:5] offset:128
	global_load_dword v237, v9, s[4:5] offset:160
	global_load_dword v238, v9, s[4:5] offset:192
	global_load_dword v239, v9, s[4:5] offset:224
	global_load_dword v240, v9, s[4:5] offset:256
	global_load_dword v241, v9, s[4:5] offset:288
	global_load_dword v242, v9, s[4:5] offset:320
	global_load_dword v243, v9, s[4:5] offset:352
	global_load_dword v244, v9, s[4:5] offset:384
	global_load_dword v245, v9, s[4:5] offset:416
	global_load_dword v246, v9, s[4:5] offset:448
	global_load_dword v247, v9, s[4:5] offset:480
	s_waitcnt vmcnt(16)
	v_lshl_add_u32 v11, v100, 10, v2
	global_load_dwordx4 v[116:119], v11, s[6:7]
	v_lshl_add_u32 v11, v101, 10, v2
	global_load_dwordx4 v[120:123], v11, s[6:7]
	v_lshl_add_u32 v11, v102, 10, v2
	global_load_dwordx4 v[124:127], v11, s[6:7]
	v_lshl_add_u32 v11, v103, 10, v2
	global_load_dwordx4 v[128:131], v11, s[6:7]
	v_lshl_add_u32 v11, v104, 10, v2
	global_load_dwordx4 v[132:135], v11, s[6:7]
	v_lshl_add_u32 v11, v105, 10, v2
	global_load_dwordx4 v[136:139], v11, s[6:7]
	v_lshl_add_u32 v11, v106, 10, v2
	global_load_dwordx4 v[140:143], v11, s[6:7]
	v_lshl_add_u32 v11, v107, 10, v2
	global_load_dwordx4 v[144:147], v11, s[6:7]
	v_lshl_add_u32 v11, v108, 10, v2
	global_load_dwordx4 v[180:183], v11, s[6:7]
	v_lshl_add_u32 v11, v109, 10, v2
	global_load_dwordx4 v[184:187], v11, s[6:7]
	v_lshl_add_u32 v11, v110, 10, v2
	global_load_dwordx4 v[188:191], v11, s[6:7]
	v_lshl_add_u32 v11, v111, 10, v2
	global_load_dwordx4 v[192:195], v11, s[6:7]
	v_lshl_add_u32 v11, v112, 10, v2
	global_load_dwordx4 v[196:199], v11, s[6:7]
	v_lshl_add_u32 v11, v113, 10, v2
	global_load_dwordx4 v[200:203], v11, s[6:7]
	v_lshl_add_u32 v11, v114, 10, v2
	global_load_dwordx4 v[204:207], v11, s[6:7]
	v_lshl_add_u32 v11, v115, 10, v2
	global_load_dwordx4 v[208:211], v11, s[6:7]
	s_mov_b32 s18, 0
	s_waitcnt lgkmcnt(0)
; DI void phase_peer_down(const Params& p) {
;     ...
;       for (int bi = 0; bi < 8; ++bi) {
;         u32x4 dr[8];
; #pragma unroll
;         for (int k = 0; k < 8; ++k) {
;           const int er = __builtin_amdgcn_readlane(ev, bi * 8 + k);
;           dr[k] = *reinterpret_cast<const u32x4*>(exd + (size_t)er * 1024 + lane * 16);
;         }
;         const int pmine = bi * 8 + (lane & 7);
;         const int emine = __shfl(ev, pmine);
;         const float gsel = __shfl(gv, pmine);
;         const float sd = esc[emine];
;         const float su = esc[16384 + emine];
;         float part[8];
; #pragma unroll
;         for (int k = 0; k < 8; ++k) {
;           float a0 = 0.f, a1 = 0.f;
; #pragma unroll
;           for (int w = 0; w < 4; ++w) {
;             f2_t lo = __builtin_amdgcn_cvt_pk_f32_fp8((int)dr[k][w], false);
;             f2_t hi = __builtin_amdgcn_cvt_pk_f32_fp8((int)dr[k][w], true);
;             a0 = fmaf(lo[0], x[4 * w], a0); a1 = fmaf(lo[1], x[4 * w + 1], a1);
;             a0 = fmaf(hi[0], x[4 * w + 2], a0); a1 = fmaf(hi[1], x[4 * w + 3], a1);
;           }
;           part[k] = a0 + a1;
;         }
;         const float r1 = reduce8(part, lane) * sd;
;         const bool mine = (lane >> 3) == bi;
;         racc = mine ? r1 : racc; gacc = mine ? gsel * su : gacc;
;       }
.Lpd_loop:
	s_add_i32 s20, s18, 1
	s_min_i32 s20, s20, 0x7f
	s_lshr_b32 s21, s20, 4
	s_and_b32 s22, s20, 15
	s_add_i32 s23, s18, 2
	s_min_i32 s23, s23, 0x7f
	s_and_b32 s24, s23, 15
	s_and_b32 s26, s18, 15
	s_lshl_b32 s22, s22, 11
	s_lshl_b32 s24, s24, 11
	s_lshl_b32 s27, s21, 8
	s_lshl_b32 s28, s21, 7
	s_lshl_b32 s29, s26, 9
	v_add_u32_e32 v5, s22, v64
	v_add_u32_e32 v6, s24, v64
	v_add_u32_e32 v10, s29, v4
	v_lshl_add_u32 v7, v5, 11, v3
	v_add_u32_e32 v7, s27, v7
	v_add_u32_e32 v8, s28, v2
	v_lshl_add_u32 v9, v6, 9, v1
	ds_read_b64 v[98:99], v10
	s_waitcnt vmcnt(16)
	v_lshlrev_b32_e32 v28, 16, v20
	v_and_b32_e32 v29, 0xffff0000, v20
	v_lshlrev_b32_e32 v30, 16, v21
	v_and_b32_e32 v31, 0xffff0000, v21
	v_lshlrev_b32_e32 v32, 16, v22
	v_and_b32_e32 v33, 0xffff0000, v22
	v_lshlrev_b32_e32 v34, 16, v23
	v_and_b32_e32 v35, 0xffff0000, v23
	v_lshlrev_b32_e32 v36, 16, v24
	v_and_b32_e32 v37, 0xffff0000, v24
	v_lshlrev_b32_e32 v38, 16, v25
	v_and_b32_e32 v39, 0xffff0000, v25
	v_lshlrev_b32_e32 v40, 16, v26
	v_and_b32_e32 v41, 0xffff0000, v26
	v_lshlrev_b32_e32 v42, 16, v27
	v_and_b32_e32 v43, 0xffff0000, v27
	global_load_dwordx4 v[20:23], v7, s[8:9]
	global_load_dwordx4 v[24:27], v7, s[8:9] offset:16
	global_load_dword v100, v9, s[4:5] offset:0
	global_load_dword v101, v9, s[4:5] offset:32
	global_load_dword v102, v9, s[4:5] offset:64
	global_load_dword v103, v9, s[4:5] offset:96
	global_load_dword v104, v9, s[4:5] offset:128
	global_load_dword v105, v9, s[4:5] offset:160
	global_load_dword v106, v9, s[4:5] offset:192
	global_load_dword v107, v9, s[4:5] offset:224
	global_load_dword v108, v9, s[4:5] offset:256
	global_load_dword v109, v9, s[4:5] offset:288
	global_load_dword v110, v9, s[4:5] offset:320
	global_load_dword v111, v9, s[4:5] offset:352
	global_load_dword v112, v9, s[4:5] offset:384
	global_load_dword v113, v9, s[4:5] offset:416
	global_load_dword v114, v9, s[4:5] offset:448
	global_load_dword v115, v9, s[4:5] offset:480
	s_waitcnt lgkmcnt(0)
	s_waitcnt vmcnt(32)
	v_cvt_pk_f32_fp8_e32 v[44:45], v116
	v_cvt_pk_f32_fp8_sdwa v[46:47], v116 src0_sel:WORD_1
	v_cvt_pk_f32_fp8_e32 v[48:49], v117
	v_cvt_pk_f32_fp8_sdwa v[50:51], v117 src0_sel:WORD_1
	v_cvt_pk_f32_fp8_e32 v[52:53], v118
	v_cvt_pk_f32_fp8_sdwa v[54:55], v118 src0_sel:WORD_1
	v_cvt_pk_f32_fp8_e32 v[56:57], v119
	v_cvt_pk_f32_fp8_sdwa v[58:59], v119 src0_sel:WORD_1
	v_cvt_pk_f32_fp8_e32 v[66:67], v120
	v_cvt_pk_f32_fp8_sdwa v[68:69], v120 src0_sel:WORD_1
	v_cvt_pk_f32_fp8_e32 v[70:71], v121
	v_cvt_pk_f32_fp8_sdwa v[72:73], v121 src0_sel:WORD_1
	v_cvt_pk_f32_fp8_e32 v[74:75], v122
	v_cvt_pk_f32_fp8_sdwa v[76:77], v122 src0_sel:WORD_1
	v_cvt_pk_f32_fp8_e32 v[78:79], v123
	v_cvt_pk_f32_fp8_sdwa v[80:81], v123 src0_sel:WORD_1
	v_pk_mul_f32 v[82:83], v[44:45], v[28:29]
	v_pk_mul_f32 v[86:87], v[66:67], v[28:29]
	v_pk_mul_f32 v[84:85], v[46:47], v[30:31]
	v_pk_mul_f32 v[88:89], v[68:69], v[30:31]
	v_pk_fma_f32 v[82:83], v[48:49], v[32:33], v[82:83]
	v_pk_fma_f32 v[86:87], v[70:71], v[32:33], v[86:87]
	v_pk_fma_f32 v[84:85], v[50:51], v[34:35], v[84:85]
	v_pk_fma_f32 v[88:89], v[72:73], v[34:35], v[88:89]
	v_pk_fma_f32 v[82:83], v[52:53], v[36:37], v[82:83]
	v_pk_fma_f32 v[86:87], v[74:75], v[36:37], v[86:87]
	v_pk_fma_f32 v[84:85], v[54:55], v[38:39], v[84:85]
	v_pk_fma_f32 v[88:89], v[76:77], v[38:39], v[88:89]
	v_pk_fma_f32 v[82:83], v[56:57], v[40:41], v[82:83]
	v_pk_fma_f32 v[86:87], v[78:79], v[40:41], v[86:87]
	v_pk_fma_f32 v[84:85], v[58:59], v[42:43], v[84:85]
	v_pk_fma_f32 v[88:89], v[80:81], v[42:43], v[88:89]
	v_pk_add_f32 v[82:83], v[82:83], v[84:85]
	v_pk_add_f32 v[86:87], v[86:87], v[88:89]
	v_lshl_add_u32 v11, v232, 10, v8
	v_add_f32_e32 v90, v82, v83
	v_add_f32_e32 v94, v86, v87
	global_load_dwordx4 v[116:119], v11, s[6:7]
	v_lshl_add_u32 v65, v233, 10, v8
	v_add_f32_dpp v91, v90, v90 quad_perm:[1,0,3,2] row_mask:0xf bank_mask:0xf
	v_add_f32_dpp v95, v94, v94 quad_perm:[1,0,3,2] row_mask:0xf bank_mask:0xf
	global_load_dwordx4 v[120:123], v65, s[6:7]
	v_add_f32_dpp v92, v91, v91 quad_perm:[2,3,0,1] row_mask:0xf bank_mask:0xf
	v_add_f32_dpp v96, v95, v95 quad_perm:[2,3,0,1] row_mask:0xf bank_mask:0xf
	s_nop 0
	v_add_f32_dpp v93, v92, v92 row_half_mirror row_mask:0xf bank_mask:0xf
	v_add_f32_dpp v97, v96, v96 row_half_mirror row_mask:0xf bank_mask:0xf
	v_fmac_f32_e32 v98, v93, v12
	v_fmac_f32_e32 v98, v97, v13
	s_waitcnt vmcnt(32)
	v_cvt_pk_f32_fp8_e32 v[44:45], v124
	v_cvt_pk_f32_fp8_sdwa v[46:47], v124 src0_sel:WORD_1
	v_cvt_pk_f32_fp8_e32 v[48:49], v125
	v_cvt_pk_f32_fp8_sdwa v[50:51], v125 src0_sel:WORD_1
	v_cvt_pk_f32_fp8_e32 v[52:53], v126
	v_cvt_pk_f32_fp8_sdwa v[54:55], v126 src0_sel:WORD_1
	v_cvt_pk_f32_fp8_e32 v[56:57], v127
	v_cvt_pk_f32_fp8_sdwa v[58:59], v127 src0_sel:WORD_1
	v_cvt_pk_f32_fp8_e32 v[66:67], v128
	v_cvt_pk_f32_fp8_sdwa v[68:69], v128 src0_sel:WORD_1
	v_cvt_pk_f32_fp8_e32 v[70:71], v129
	v_cvt_pk_f32_fp8_sdwa v[72:73], v129 src0_sel:WORD_1
	v_cvt_pk_f32_fp8_e32 v[74:75], v130
	v_cvt_pk_f32_fp8_sdwa v[76:77], v130 src0_sel:WORD_1
	v_cvt_pk_f32_fp8_e32 v[78:79], v131
	v_cvt_pk_f32_fp8_sdwa v[80:81], v131 src0_sel:WORD_1
	v_pk_mul_f32 v[82:83], v[44:45], v[28:29]
	v_pk_mul_f32 v[86:87], v[66:67], v[28:29]
	v_pk_mul_f32 v[84:85], v[46:47], v[30:31]
	v_pk_mul_f32 v[88:89], v[68:69], v[30:31]
	v_pk_fma_f32 v[82:83], v[48:49], v[32:33], v[82:83]
	v_pk_fma_f32 v[86:87], v[70:71], v[32:33], v[86:87]
	v_pk_fma_f32 v[84:85], v[50:51], v[34:35], v[84:85]
	v_pk_fma_f32 v[88:89], v[72:73], v[34:35], v[88:89]
	v_pk_fma_f32 v[82:83], v[52:53], v[36:37], v[82:83]
	v_pk_fma_f32 v[86:87], v[74:75], v[36:37], v[86:87]
	v_pk_fma_f32 v[84:85], v[54:55], v[38:39], v[84:85]
	v_pk_fma_f32 v[88:89], v[76:77], v[38:39], v[88:89]
	v_pk_fma_f32 v[82:83], v[56:57], v[40:41], v[82:83]
	v_pk_fma_f32 v[86:87], v[78:79], v[40:41], v[86:87]
	v_pk_fma_f32 v[84:85], v[58:59], v[42:43], v[84:85]
	v_pk_fma_f32 v[88:89], v[80:81], v[42:43], v[88:89]
	v_pk_add_f32 v[82:83], v[82:83], v[84:85]
	v_pk_add_f32 v[86:87], v[86:87], v[88:89]
	v_lshl_add_u32 v11, v234, 10, v8
	v_add_f32_e32 v90, v82, v83
	v_add_f32_e32 v94, v86, v87
	global_load_dwordx4 v[124:127], v11, s[6:7]
	v_lshl_add_u32 v65, v235, 10, v8
	v_add_f32_dpp v91, v90, v90 quad_perm:[1,0,3,2] row_mask:0xf bank_mask:0xf
	v_add_f32_dpp v95, v94, v94 quad_perm:[1,0,3,2] row_mask:0xf bank_mask:0xf
	global_load_dwordx4 v[128:131], v65, s[6:7]
	v_add_f32_dpp v92, v91, v91 quad_perm:[2,3,0,1] row_mask:0xf bank_mask:0xf
	v_add_f32_dpp v96, v95, v95 quad_perm:[2,3,0,1] row_mask:0xf bank_mask:0xf
	s_nop 0
	v_add_f32_dpp v93, v92, v92 row_half_mirror row_mask:0xf bank_mask:0xf
	v_add_f32_dpp v97, v96, v96 row_half_mirror row_mask:0xf bank_mask:0xf
	v_fmac_f32_e32 v98, v93, v14
	v_fmac_f32_e32 v98, v97, v15
	s_waitcnt vmcnt(32)
; DI void phase_peer_down(const Params& p) {
;     ...
;       for (int bi = 0; bi < 8; ++bi) {
;         u32x4 dr[8];
; #pragma unroll
;         for (int k = 0; k < 8; ++k) {
;           const int er = __builtin_amdgcn_readlane(ev, bi * 8 + k);
;           dr[k] = *reinterpret_cast<const u32x4*>(exd + (size_t)er * 1024 + lane * 16);
;         }
;         const int pmine = bi * 8 + (lane & 7);
;         const int emine = __shfl(ev, pmine);
;         const float gsel = __shfl(gv, pmine);
;         const float sd = esc[emine];
;         const float su = esc[16384 + emine];
;         float part[8];
; #pragma unroll
;         for (int k = 0; k < 8; ++k) {
;           float a0 = 0.f, a1 = 0.f;
; #pragma unroll
;           for (int w = 0; w < 4; ++w) {
;             f2_t lo = __builtin_amdgcn_cvt_pk_f32_fp8((int)dr[k][w], false);
;             f2_t hi = __builtin_amdgcn_cvt_pk_f32_fp8((int)dr[k][w], true);
;             a0 = fmaf(lo[0], x[4 * w], a0); a1 = fmaf(lo[1], x[4 * w + 1], a1);
;             a0 = fmaf(hi[0], x[4 * w + 2], a0); a1 = fmaf(hi[1], x[4 * w + 3], a1);
;           }
;           part[k] = a0 + a1;
;         }
;         const float r1 = reduce8(part, lane) * sd;
;         const bool mine = (lane >> 3) == bi;
;         racc = mine ? r1 : racc; gacc = mine ? gsel * su : gacc;
;       }
	v_cvt_pk_f32_fp8_e32 v[44:45], v132
	v_cvt_pk_f32_fp8_sdwa v[46:47], v132 src0_sel:WORD_1
	v_cvt_pk_f32_fp8_e32 v[48:49], v133
	v_cvt_pk_f32_fp8_sdwa v[50:51], v133 src0_sel:WORD_1
	v_cvt_pk_f32_fp8_e32 v[52:53], v134
	v_cvt_pk_f32_fp8_sdwa v[54:55], v134 src0_sel:WORD_1
	v_cvt_pk_f32_fp8_e32 v[56:57], v135
	v_cvt_pk_f32_fp8_sdwa v[58:59], v135 src0_sel:WORD_1
	v_cvt_pk_f32_fp8_e32 v[66:67], v136
	v_cvt_pk_f32_fp8_sdwa v[68:69], v136 src0_sel:WORD_1
	v_cvt_pk_f32_fp8_e32 v[70:71], v137
	v_cvt_pk_f32_fp8_sdwa v[72:73], v137 src0_sel:WORD_1
	v_cvt_pk_f32_fp8_e32 v[74:75], v138
	v_cvt_pk_f32_fp8_sdwa v[76:77], v138 src0_sel:WORD_1
	v_cvt_pk_f32_fp8_e32 v[78:79], v139
	v_cvt_pk_f32_fp8_sdwa v[80:81], v139 src0_sel:WORD_1
	v_pk_mul_f32 v[82:83], v[44:45], v[28:29]
	v_pk_mul_f32 v[86:87], v[66:67], v[28:29]
	v_pk_mul_f32 v[84:85], v[46:47], v[30:31]
	v_pk_mul_f32 v[88:89], v[68:69], v[30:31]
	v_pk_fma_f32 v[82:83], v[48:49], v[32:33], v[82:83]
	v_pk_fma_f32 v[86:87], v[70:71], v[32:33], v[86:87]
	v_pk_fma_f32 v[84:85], v[50:51], v[34:35], v[84:85]
	v_pk_fma_f32 v[88:89], v[72:73], v[34:35], v[88:89]
	v_pk_fma_f32 v[82:83], v[52:53], v[36:37], v[82:83]
	v_pk_fma_f32 v[86:87], v[74:75], v[36:37], v[86:87]
	v_pk_fma_f32 v[84:85], v[54:55], v[38:39], v[84:85]
	v_pk_fma_f32 v[88:89], v[76:77], v[38:39], v[88:89]
	v_pk_fma_f32 v[82:83], v[56:57], v[40:41], v[82:83]
	v_pk_fma_f32 v[86:87], v[78:79], v[40:41], v[86:87]
	v_pk_fma_f32 v[84:85], v[58:59], v[42:43], v[84:85]
	v_pk_fma_f32 v[88:89], v[80:81], v[42:43], v[88:89]
	v_pk_add_f32 v[82:83], v[82:83], v[84:85]
	v_pk_add_f32 v[86:87], v[86:87], v[88:89]
	v_lshl_add_u32 v11, v236, 10, v8
	v_add_f32_e32 v90, v82, v83
	v_add_f32_e32 v94, v86, v87
	global_load_dwordx4 v[132:135], v11, s[6:7]
	v_lshl_add_u32 v65, v237, 10, v8
	v_add_f32_dpp v91, v90, v90 quad_perm:[1,0,3,2] row_mask:0xf bank_mask:0xf
	v_add_f32_dpp v95, v94, v94 quad_perm:[1,0,3,2] row_mask:0xf bank_mask:0xf
	global_load_dwordx4 v[136:139], v65, s[6:7]
	v_add_f32_dpp v92, v91, v91 quad_perm:[2,3,0,1] row_mask:0xf bank_mask:0xf
	v_add_f32_dpp v96, v95, v95 quad_perm:[2,3,0,1] row_mask:0xf bank_mask:0xf
	s_nop 0
	v_add_f32_dpp v93, v92, v92 row_half_mirror row_mask:0xf bank_mask:0xf
	v_add_f32_dpp v97, v96, v96 row_half_mirror row_mask:0xf bank_mask:0xf
	v_fmac_f32_e32 v98, v93, v16
	v_fmac_f32_e32 v98, v97, v17
	s_waitcnt vmcnt(32)
	v_cvt_pk_f32_fp8_e32 v[44:45], v140
	v_cvt_pk_f32_fp8_sdwa v[46:47], v140 src0_sel:WORD_1
	v_cvt_pk_f32_fp8_e32 v[48:49], v141
	v_cvt_pk_f32_fp8_sdwa v[50:51], v141 src0_sel:WORD_1
	v_cvt_pk_f32_fp8_e32 v[52:53], v142
	v_cvt_pk_f32_fp8_sdwa v[54:55], v142 src0_sel:WORD_1
	v_cvt_pk_f32_fp8_e32 v[56:57], v143
	v_cvt_pk_f32_fp8_sdwa v[58:59], v143 src0_sel:WORD_1
	v_cvt_pk_f32_fp8_e32 v[66:67], v144
	v_cvt_pk_f32_fp8_sdwa v[68:69], v144 src0_sel:WORD_1
	v_cvt_pk_f32_fp8_e32 v[70:71], v145
	v_cvt_pk_f32_fp8_sdwa v[72:73], v145 src0_sel:WORD_1
	v_cvt_pk_f32_fp8_e32 v[74:75], v146
	v_cvt_pk_f32_fp8_sdwa v[76:77], v146 src0_sel:WORD_1
	v_cvt_pk_f32_fp8_e32 v[78:79], v147
	v_cvt_pk_f32_fp8_sdwa v[80:81], v147 src0_sel:WORD_1
	v_pk_mul_f32 v[82:83], v[44:45], v[28:29]
	v_pk_mul_f32 v[86:87], v[66:67], v[28:29]
	v_pk_mul_f32 v[84:85], v[46:47], v[30:31]
	v_pk_mul_f32 v[88:89], v[68:69], v[30:31]
	v_pk_fma_f32 v[82:83], v[48:49], v[32:33], v[82:83]
	v_pk_fma_f32 v[86:87], v[70:71], v[32:33], v[86:87]
	v_pk_fma_f32 v[84:85], v[50:51], v[34:35], v[84:85]
	v_pk_fma_f32 v[88:89], v[72:73], v[34:35], v[88:89]
	v_pk_fma_f32 v[82:83], v[52:53], v[36:37], v[82:83]
	v_pk_fma_f32 v[86:87], v[74:75], v[36:37], v[86:87]
	v_pk_fma_f32 v[84:85], v[54:55], v[38:39], v[84:85]
	v_pk_fma_f32 v[88:89], v[76:77], v[38:39], v[88:89]
	v_pk_fma_f32 v[82:83], v[56:57], v[40:41], v[82:83]
	v_pk_fma_f32 v[86:87], v[78:79], v[40:41], v[86:87]
	v_pk_fma_f32 v[84:85], v[58:59], v[42:43], v[84:85]
	v_pk_fma_f32 v[88:89], v[80:81], v[42:43], v[88:89]
	v_pk_add_f32 v[82:83], v[82:83], v[84:85]
	v_pk_add_f32 v[86:87], v[86:87], v[88:89]
	v_lshl_add_u32 v11, v238, 10, v8
	v_add_f32_e32 v90, v82, v83
	v_add_f32_e32 v94, v86, v87
	global_load_dwordx4 v[140:143], v11, s[6:7]
	v_lshl_add_u32 v65, v239, 10, v8
	v_add_f32_dpp v91, v90, v90 quad_perm:[1,0,3,2] row_mask:0xf bank_mask:0xf
	v_add_f32_dpp v95, v94, v94 quad_perm:[1,0,3,2] row_mask:0xf bank_mask:0xf
	global_load_dwordx4 v[144:147], v65, s[6:7]
	v_add_f32_dpp v92, v91, v91 quad_perm:[2,3,0,1] row_mask:0xf bank_mask:0xf
	v_add_f32_dpp v96, v95, v95 quad_perm:[2,3,0,1] row_mask:0xf bank_mask:0xf
	s_nop 0
	v_add_f32_dpp v93, v92, v92 row_half_mirror row_mask:0xf bank_mask:0xf
	v_add_f32_dpp v97, v96, v96 row_half_mirror row_mask:0xf bank_mask:0xf
	v_fmac_f32_e32 v98, v93, v18
	v_fmac_f32_e32 v98, v97, v19
	s_waitcnt vmcnt(32)
; DI void phase_peer_down(const Params& p) {
;     ...
;       for (int bi = 0; bi < 8; ++bi) {
;         u32x4 dr[8];
; #pragma unroll
;         for (int k = 0; k < 8; ++k) {
;           const int er = __builtin_amdgcn_readlane(ev, bi * 8 + k);
;           dr[k] = *reinterpret_cast<const u32x4*>(exd + (size_t)er * 1024 + lane * 16);
;         }
;         const int pmine = bi * 8 + (lane & 7);
;         const int emine = __shfl(ev, pmine);
;         const float gsel = __shfl(gv, pmine);
;         const float sd = esc[emine];
;         const float su = esc[16384 + emine];
;         float part[8];
; #pragma unroll
;         for (int k = 0; k < 8; ++k) {
;           float a0 = 0.f, a1 = 0.f;
; #pragma unroll
;           for (int w = 0; w < 4; ++w) {
;             f2_t lo = __builtin_amdgcn_cvt_pk_f32_fp8((int)dr[k][w], false);
;             f2_t hi = __builtin_amdgcn_cvt_pk_f32_fp8((int)dr[k][w], true);
;             a0 = fmaf(lo[0], x[4 * w], a0); a1 = fmaf(lo[1], x[4 * w + 1], a1);
;             a0 = fmaf(hi[0], x[4 * w + 2], a0); a1 = fmaf(hi[1], x[4 * w + 3], a1);
;           }
;           part[k] = a0 + a1;
;         }
;         const float r1 = reduce8(part, lane) * sd;
;         const bool mine = (lane >> 3) == bi;
;         racc = mine ? r1 : racc; gacc = mine ? gsel * su : gacc;
;       }
	v_cvt_pk_f32_fp8_e32 v[44:45], v180
	v_cvt_pk_f32_fp8_sdwa v[46:47], v180 src0_sel:WORD_1
	v_cvt_pk_f32_fp8_e32 v[48:49], v181
	v_cvt_pk_f32_fp8_sdwa v[50:51], v181 src0_sel:WORD_1
	v_cvt_pk_f32_fp8_e32 v[52:53], v182
	v_cvt_pk_f32_fp8_sdwa v[54:55], v182 src0_sel:WORD_1
	v_cvt_pk_f32_fp8_e32 v[56:57], v183
	v_cvt_pk_f32_fp8_sdwa v[58:59], v183 src0_sel:WORD_1
	v_cvt_pk_f32_fp8_e32 v[66:67], v184
	v_cvt_pk_f32_fp8_sdwa v[68:69], v184 src0_sel:WORD_1
	v_cvt_pk_f32_fp8_e32 v[70:71], v185
	v_cvt_pk_f32_fp8_sdwa v[72:73], v185 src0_sel:WORD_1
	v_cvt_pk_f32_fp8_e32 v[74:75], v186
	v_cvt_pk_f32_fp8_sdwa v[76:77], v186 src0_sel:WORD_1
	v_cvt_pk_f32_fp8_e32 v[78:79], v187
	v_cvt_pk_f32_fp8_sdwa v[80:81], v187 src0_sel:WORD_1
	v_pk_mul_f32 v[82:83], v[44:45], v[28:29]
	v_pk_mul_f32 v[86:87], v[66:67], v[28:29]
	v_pk_mul_f32 v[84:85], v[46:47], v[30:31]
	v_pk_mul_f32 v[88:89], v[68:69], v[30:31]
	v_pk_fma_f32 v[82:83], v[48:49], v[32:33], v[82:83]
	v_pk_fma_f32 v[86:87], v[70:71], v[32:33], v[86:87]
	v_pk_fma_f32 v[84:85], v[50:51], v[34:35], v[84:85]
	v_pk_fma_f32 v[88:89], v[72:73], v[34:35], v[88:89]
	v_pk_fma_f32 v[82:83], v[52:53], v[36:37], v[82:83]
	v_pk_fma_f32 v[86:87], v[74:75], v[36:37], v[86:87]
	v_pk_fma_f32 v[84:85], v[54:55], v[38:39], v[84:85]
	v_pk_fma_f32 v[88:89], v[76:77], v[38:39], v[88:89]
	v_pk_fma_f32 v[82:83], v[56:57], v[40:41], v[82:83]
	v_pk_fma_f32 v[86:87], v[78:79], v[40:41], v[86:87]
	v_pk_fma_f32 v[84:85], v[58:59], v[42:43], v[84:85]
	v_pk_fma_f32 v[88:89], v[80:81], v[42:43], v[88:89]
	v_pk_add_f32 v[82:83], v[82:83], v[84:85]
	v_pk_add_f32 v[86:87], v[86:87], v[88:89]
	v_lshl_add_u32 v11, v240, 10, v8
	v_add_f32_e32 v90, v82, v83
	v_add_f32_e32 v94, v86, v87
	global_load_dwordx4 v[180:183], v11, s[6:7]
	v_lshl_add_u32 v65, v241, 10, v8
	v_add_f32_dpp v91, v90, v90 quad_perm:[1,0,3,2] row_mask:0xf bank_mask:0xf
	v_add_f32_dpp v95, v94, v94 quad_perm:[1,0,3,2] row_mask:0xf bank_mask:0xf
	global_load_dwordx4 v[184:187], v65, s[6:7]
	v_add_f32_dpp v92, v91, v91 quad_perm:[2,3,0,1] row_mask:0xf bank_mask:0xf
	v_add_f32_dpp v96, v95, v95 quad_perm:[2,3,0,1] row_mask:0xf bank_mask:0xf
	s_nop 0
	v_add_f32_dpp v93, v92, v92 row_half_mirror row_mask:0xf bank_mask:0xf
	v_add_f32_dpp v97, v96, v96 row_half_mirror row_mask:0xf bank_mask:0xf
	v_fmac_f32_e32 v99, v93, v12
	v_fmac_f32_e32 v99, v97, v13
	s_waitcnt vmcnt(32)
	v_cvt_pk_f32_fp8_e32 v[44:45], v188
	v_cvt_pk_f32_fp8_sdwa v[46:47], v188 src0_sel:WORD_1
	v_cvt_pk_f32_fp8_e32 v[48:49], v189
	v_cvt_pk_f32_fp8_sdwa v[50:51], v189 src0_sel:WORD_1
	v_cvt_pk_f32_fp8_e32 v[52:53], v190
	v_cvt_pk_f32_fp8_sdwa v[54:55], v190 src0_sel:WORD_1
	v_cvt_pk_f32_fp8_e32 v[56:57], v191
	v_cvt_pk_f32_fp8_sdwa v[58:59], v191 src0_sel:WORD_1
	v_cvt_pk_f32_fp8_e32 v[66:67], v192
	v_cvt_pk_f32_fp8_sdwa v[68:69], v192 src0_sel:WORD_1
	v_cvt_pk_f32_fp8_e32 v[70:71], v193
	v_cvt_pk_f32_fp8_sdwa v[72:73], v193 src0_sel:WORD_1
	v_cvt_pk_f32_fp8_e32 v[74:75], v194
	v_cvt_pk_f32_fp8_sdwa v[76:77], v194 src0_sel:WORD_1
	v_cvt_pk_f32_fp8_e32 v[78:79], v195
	v_cvt_pk_f32_fp8_sdwa v[80:81], v195 src0_sel:WORD_1
	v_pk_mul_f32 v[82:83], v[44:45], v[28:29]
	v_pk_mul_f32 v[86:87], v[66:67], v[28:29]
	v_pk_mul_f32 v[84:85], v[46:47], v[30:31]
	v_pk_mul_f32 v[88:89], v[68:69], v[30:31]
	v_pk_fma_f32 v[82:83], v[48:49], v[32:33], v[82:83]
	v_pk_fma_f32 v[86:87], v[70:71], v[32:33], v[86:87]
	v_pk_fma_f32 v[84:85], v[50:51], v[34:35], v[84:85]
	v_pk_fma_f32 v[88:89], v[72:73], v[34:35], v[88:89]
	v_pk_fma_f32 v[82:83], v[52:53], v[36:37], v[82:83]
	v_pk_fma_f32 v[86:87], v[74:75], v[36:37], v[86:87]
	v_pk_fma_f32 v[84:85], v[54:55], v[38:39], v[84:85]
	v_pk_fma_f32 v[88:89], v[76:77], v[38:39], v[88:89]
	v_pk_fma_f32 v[82:83], v[56:57], v[40:41], v[82:83]
	v_pk_fma_f32 v[86:87], v[78:79], v[40:41], v[86:87]
	v_pk_fma_f32 v[84:85], v[58:59], v[42:43], v[84:85]
	v_pk_fma_f32 v[88:89], v[80:81], v[42:43], v[88:89]
	v_pk_add_f32 v[82:83], v[82:83], v[84:85]
	v_pk_add_f32 v[86:87], v[86:87], v[88:89]
	v_lshl_add_u32 v11, v242, 10, v8
	v_add_f32_e32 v90, v82, v83
	v_add_f32_e32 v94, v86, v87
	global_load_dwordx4 v[188:191], v11, s[6:7]
	v_lshl_add_u32 v65, v243, 10, v8
	v_add_f32_dpp v91, v90, v90 quad_perm:[1,0,3,2] row_mask:0xf bank_mask:0xf
	v_add_f32_dpp v95, v94, v94 quad_perm:[1,0,3,2] row_mask:0xf bank_mask:0xf
	global_load_dwordx4 v[192:195], v65, s[6:7]
	v_add_f32_dpp v92, v91, v91 quad_perm:[2,3,0,1] row_mask:0xf bank_mask:0xf
	v_add_f32_dpp v96, v95, v95 quad_perm:[2,3,0,1] row_mask:0xf bank_mask:0xf
	s_nop 0
	v_add_f32_dpp v93, v92, v92 row_half_mirror row_mask:0xf bank_mask:0xf
	v_add_f32_dpp v97, v96, v96 row_half_mirror row_mask:0xf bank_mask:0xf
	v_fmac_f32_e32 v99, v93, v14
	v_fmac_f32_e32 v99, v97, v15
	s_waitcnt vmcnt(32)
; DI void phase_peer_down(const Params& p) {
;     ...
;       for (int bi = 0; bi < 8; ++bi) {
;         u32x4 dr[8];
; #pragma unroll
;         for (int k = 0; k < 8; ++k) {
;           const int er = __builtin_amdgcn_readlane(ev, bi * 8 + k);
;           dr[k] = *reinterpret_cast<const u32x4*>(exd + (size_t)er * 1024 + lane * 16);
;         }
;         const int pmine = bi * 8 + (lane & 7);
;         const int emine = __shfl(ev, pmine);
;         const float gsel = __shfl(gv, pmine);
;         const float sd = esc[emine];
;         const float su = esc[16384 + emine];
;         float part[8];
; #pragma unroll
;         for (int k = 0; k < 8; ++k) {
;           float a0 = 0.f, a1 = 0.f;
; #pragma unroll
;           for (int w = 0; w < 4; ++w) {
;             f2_t lo = __builtin_amdgcn_cvt_pk_f32_fp8((int)dr[k][w], false);
;             f2_t hi = __builtin_amdgcn_cvt_pk_f32_fp8((int)dr[k][w], true);
;             a0 = fmaf(lo[0], x[4 * w], a0); a1 = fmaf(lo[1], x[4 * w + 1], a1);
;             a0 = fmaf(hi[0], x[4 * w + 2], a0); a1 = fmaf(hi[1], x[4 * w + 3], a1);
;           }
;           part[k] = a0 + a1;
;         }
;         const float r1 = reduce8(part, lane) * sd;
;         const bool mine = (lane >> 3) == bi;
;         racc = mine ? r1 : racc; gacc = mine ? gsel * su : gacc;
;       }
	v_cvt_pk_f32_fp8_e32 v[44:45], v196
	v_cvt_pk_f32_fp8_sdwa v[46:47], v196 src0_sel:WORD_1
	v_cvt_pk_f32_fp8_e32 v[48:49], v197
	v_cvt_pk_f32_fp8_sdwa v[50:51], v197 src0_sel:WORD_1
	v_cvt_pk_f32_fp8_e32 v[52:53], v198
	v_cvt_pk_f32_fp8_sdwa v[54:55], v198 src0_sel:WORD_1
	v_cvt_pk_f32_fp8_e32 v[56:57], v199
	v_cvt_pk_f32_fp8_sdwa v[58:59], v199 src0_sel:WORD_1
	v_cvt_pk_f32_fp8_e32 v[66:67], v200
	v_cvt_pk_f32_fp8_sdwa v[68:69], v200 src0_sel:WORD_1
	v_cvt_pk_f32_fp8_e32 v[70:71], v201
	v_cvt_pk_f32_fp8_sdwa v[72:73], v201 src0_sel:WORD_1
	v_cvt_pk_f32_fp8_e32 v[74:75], v202
	v_cvt_pk_f32_fp8_sdwa v[76:77], v202 src0_sel:WORD_1
	v_cvt_pk_f32_fp8_e32 v[78:79], v203
	v_cvt_pk_f32_fp8_sdwa v[80:81], v203 src0_sel:WORD_1
	v_pk_mul_f32 v[82:83], v[44:45], v[28:29]
	v_pk_mul_f32 v[86:87], v[66:67], v[28:29]
	v_pk_mul_f32 v[84:85], v[46:47], v[30:31]
	v_pk_mul_f32 v[88:89], v[68:69], v[30:31]
	v_pk_fma_f32 v[82:83], v[48:49], v[32:33], v[82:83]
	v_pk_fma_f32 v[86:87], v[70:71], v[32:33], v[86:87]
	v_pk_fma_f32 v[84:85], v[50:51], v[34:35], v[84:85]
	v_pk_fma_f32 v[88:89], v[72:73], v[34:35], v[88:89]
	v_pk_fma_f32 v[82:83], v[52:53], v[36:37], v[82:83]
	v_pk_fma_f32 v[86:87], v[74:75], v[36:37], v[86:87]
	v_pk_fma_f32 v[84:85], v[54:55], v[38:39], v[84:85]
	v_pk_fma_f32 v[88:89], v[76:77], v[38:39], v[88:89]
	v_pk_fma_f32 v[82:83], v[56:57], v[40:41], v[82:83]
	v_pk_fma_f32 v[86:87], v[78:79], v[40:41], v[86:87]
	v_pk_fma_f32 v[84:85], v[58:59], v[42:43], v[84:85]
	v_pk_fma_f32 v[88:89], v[80:81], v[42:43], v[88:89]
	v_pk_add_f32 v[82:83], v[82:83], v[84:85]
	v_pk_add_f32 v[86:87], v[86:87], v[88:89]
	v_lshl_add_u32 v11, v244, 10, v8
	v_add_f32_e32 v90, v82, v83
	v_add_f32_e32 v94, v86, v87
	global_load_dwordx4 v[196:199], v11, s[6:7]
	v_lshl_add_u32 v65, v245, 10, v8
	v_add_f32_dpp v91, v90, v90 quad_perm:[1,0,3,2] row_mask:0xf bank_mask:0xf
	v_add_f32_dpp v95, v94, v94 quad_perm:[1,0,3,2] row_mask:0xf bank_mask:0xf
	global_load_dwordx4 v[200:203], v65, s[6:7]
	v_add_f32_dpp v92, v91, v91 quad_perm:[2,3,0,1] row_mask:0xf bank_mask:0xf
	v_add_f32_dpp v96, v95, v95 quad_perm:[2,3,0,1] row_mask:0xf bank_mask:0xf
	s_nop 0
	v_add_f32_dpp v93, v92, v92 row_half_mirror row_mask:0xf bank_mask:0xf
	v_add_f32_dpp v97, v96, v96 row_half_mirror row_mask:0xf bank_mask:0xf
	v_fmac_f32_e32 v99, v93, v16
	v_fmac_f32_e32 v99, v97, v17
	s_waitcnt vmcnt(32)
	v_cvt_pk_f32_fp8_e32 v[44:45], v204
	v_cvt_pk_f32_fp8_sdwa v[46:47], v204 src0_sel:WORD_1
	v_cvt_pk_f32_fp8_e32 v[48:49], v205
	v_cvt_pk_f32_fp8_sdwa v[50:51], v205 src0_sel:WORD_1
	v_cvt_pk_f32_fp8_e32 v[52:53], v206
	v_cvt_pk_f32_fp8_sdwa v[54:55], v206 src0_sel:WORD_1
	v_cvt_pk_f32_fp8_e32 v[56:57], v207
	v_cvt_pk_f32_fp8_sdwa v[58:59], v207 src0_sel:WORD_1
	v_cvt_pk_f32_fp8_e32 v[66:67], v208
	v_cvt_pk_f32_fp8_sdwa v[68:69], v208 src0_sel:WORD_1
	v_cvt_pk_f32_fp8_e32 v[70:71], v209
	v_cvt_pk_f32_fp8_sdwa v[72:73], v209 src0_sel:WORD_1
	v_cvt_pk_f32_fp8_e32 v[74:75], v210
	v_cvt_pk_f32_fp8_sdwa v[76:77], v210 src0_sel:WORD_1
	v_cvt_pk_f32_fp8_e32 v[78:79], v211
	v_cvt_pk_f32_fp8_sdwa v[80:81], v211 src0_sel:WORD_1
	v_pk_mul_f32 v[82:83], v[44:45], v[28:29]
	v_pk_mul_f32 v[86:87], v[66:67], v[28:29]
	v_pk_mul_f32 v[84:85], v[46:47], v[30:31]
	v_pk_mul_f32 v[88:89], v[68:69], v[30:31]
	v_pk_fma_f32 v[82:83], v[48:49], v[32:33], v[82:83]
	v_pk_fma_f32 v[86:87], v[70:71], v[32:33], v[86:87]
	v_pk_fma_f32 v[84:85], v[50:51], v[34:35], v[84:85]
	v_pk_fma_f32 v[88:89], v[72:73], v[34:35], v[88:89]
	v_pk_fma_f32 v[82:83], v[52:53], v[36:37], v[82:83]
	v_pk_fma_f32 v[86:87], v[74:75], v[36:37], v[86:87]
	v_pk_fma_f32 v[84:85], v[54:55], v[38:39], v[84:85]
	v_pk_fma_f32 v[88:89], v[76:77], v[38:39], v[88:89]
	v_pk_fma_f32 v[82:83], v[56:57], v[40:41], v[82:83]
	v_pk_fma_f32 v[86:87], v[78:79], v[40:41], v[86:87]
	v_pk_fma_f32 v[84:85], v[58:59], v[42:43], v[84:85]
	v_pk_fma_f32 v[88:89], v[80:81], v[42:43], v[88:89]
	v_pk_add_f32 v[82:83], v[82:83], v[84:85]
	v_pk_add_f32 v[86:87], v[86:87], v[88:89]
	v_lshl_add_u32 v11, v246, 10, v8
	v_add_f32_e32 v90, v82, v83
	v_add_f32_e32 v94, v86, v87
	global_load_dwordx4 v[204:207], v11, s[6:7]
	v_lshl_add_u32 v65, v247, 10, v8
	v_add_f32_dpp v91, v90, v90 quad_perm:[1,0,3,2] row_mask:0xf bank_mask:0xf
	v_add_f32_dpp v95, v94, v94 quad_perm:[1,0,3,2] row_mask:0xf bank_mask:0xf
	global_load_dwordx4 v[208:211], v65, s[6:7]
	v_add_f32_dpp v92, v91, v91 quad_perm:[2,3,0,1] row_mask:0xf bank_mask:0xf
	v_add_f32_dpp v96, v95, v95 quad_perm:[2,3,0,1] row_mask:0xf bank_mask:0xf
	s_nop 0
	v_add_f32_dpp v93, v92, v92 row_half_mirror row_mask:0xf bank_mask:0xf
	v_add_f32_dpp v97, v96, v96 row_half_mirror row_mask:0xf bank_mask:0xf
	v_fmac_f32_e32 v99, v93, v18
	v_fmac_f32_e32 v99, v97, v19
	ds_write_b64 v10, v[98:99]
	s_add_i32 s18, s18, 1
	s_add_i32 s20, s18, 1
	s_min_i32 s20, s20, 0x7f
	s_lshr_b32 s21, s20, 4
	s_and_b32 s22, s20, 15
	s_add_i32 s23, s18, 2
	s_min_i32 s23, s23, 0x7f
	s_and_b32 s24, s23, 15
	s_and_b32 s26, s18, 15
	s_lshl_b32 s22, s22, 11
	s_lshl_b32 s24, s24, 11
	s_lshl_b32 s27, s21, 8
	s_lshl_b32 s28, s21, 7
	s_lshl_b32 s29, s26, 9
	v_add_u32_e32 v5, s22, v64
	v_add_u32_e32 v6, s24, v64
	v_add_u32_e32 v10, s29, v4
	v_lshl_add_u32 v7, v5, 11, v3
	v_add_u32_e32 v7, s27, v7
	v_add_u32_e32 v8, s28, v2
	v_lshl_add_u32 v9, v6, 9, v1
	ds_read_b64 v[98:99], v10
	s_waitcnt vmcnt(16)
; DI void phase_peer_down(const Params& p) {
;     ...
;       for (int bi = 0; bi < 8; ++bi) {
;         u32x4 dr[8];
; #pragma unroll
;         for (int k = 0; k < 8; ++k) {
;           const int er = __builtin_amdgcn_readlane(ev, bi * 8 + k);
;           dr[k] = *reinterpret_cast<const u32x4*>(exd + (size_t)er * 1024 + lane * 16);
;         }
;         const int pmine = bi * 8 + (lane & 7);
;         const int emine = __shfl(ev, pmine);
;         const float gsel = __shfl(gv, pmine);
;         const float sd = esc[emine];
;         const float su = esc[16384 + emine];
;         float part[8];
; #pragma unroll
;         for (int k = 0; k < 8; ++k) {
;           float a0 = 0.f, a1 = 0.f;
; #pragma unroll
;           for (int w = 0; w < 4; ++w) {
;             f2_t lo = __builtin_amdgcn_cvt_pk_f32_fp8((int)dr[k][w], false);
;             f2_t hi = __builtin_amdgcn_cvt_pk_f32_fp8((int)dr[k][w], true);
;             a0 = fmaf(lo[0], x[4 * w], a0); a1 = fmaf(lo[1], x[4 * w + 1], a1);
;             a0 = fmaf(hi[0], x[4 * w + 2], a0); a1 = fmaf(hi[1], x[4 * w + 3], a1);
;           }
;           part[k] = a0 + a1;
;         }
;         const float r1 = reduce8(part, lane) * sd;
;         const bool mine = (lane >> 3) == bi;
;         racc = mine ? r1 : racc; gacc = mine ? gsel * su : gacc;
;       }
	v_lshlrev_b32_e32 v28, 16, v20
	v_and_b32_e32 v29, 0xffff0000, v20
	v_lshlrev_b32_e32 v30, 16, v21
	v_and_b32_e32 v31, 0xffff0000, v21
	v_lshlrev_b32_e32 v32, 16, v22
	v_and_b32_e32 v33, 0xffff0000, v22
	v_lshlrev_b32_e32 v34, 16, v23
	v_and_b32_e32 v35, 0xffff0000, v23
	v_lshlrev_b32_e32 v36, 16, v24
	v_and_b32_e32 v37, 0xffff0000, v24
	v_lshlrev_b32_e32 v38, 16, v25
	v_and_b32_e32 v39, 0xffff0000, v25
	v_lshlrev_b32_e32 v40, 16, v26
	v_and_b32_e32 v41, 0xffff0000, v26
	v_lshlrev_b32_e32 v42, 16, v27
	v_and_b32_e32 v43, 0xffff0000, v27
	global_load_dwordx4 v[20:23], v7, s[8:9]
	global_load_dwordx4 v[24:27], v7, s[8:9] offset:16
	global_load_dword v232, v9, s[4:5] offset:0
	global_load_dword v233, v9, s[4:5] offset:32
	global_load_dword v234, v9, s[4:5] offset:64
	global_load_dword v235, v9, s[4:5] offset:96
	global_load_dword v236, v9, s[4:5] offset:128
	global_load_dword v237, v9, s[4:5] offset:160
	global_load_dword v238, v9, s[4:5] offset:192
	global_load_dword v239, v9, s[4:5] offset:224
	global_load_dword v240, v9, s[4:5] offset:256
	global_load_dword v241, v9, s[4:5] offset:288
	global_load_dword v242, v9, s[4:5] offset:320
	global_load_dword v243, v9, s[4:5] offset:352
	global_load_dword v244, v9, s[4:5] offset:384
	global_load_dword v245, v9, s[4:5] offset:416
	global_load_dword v246, v9, s[4:5] offset:448
	global_load_dword v247, v9, s[4:5] offset:480
	s_waitcnt lgkmcnt(0)
	s_waitcnt vmcnt(32)
	v_cvt_pk_f32_fp8_e32 v[44:45], v116
	v_cvt_pk_f32_fp8_sdwa v[46:47], v116 src0_sel:WORD_1
	v_cvt_pk_f32_fp8_e32 v[48:49], v117
	v_cvt_pk_f32_fp8_sdwa v[50:51], v117 src0_sel:WORD_1
	v_cvt_pk_f32_fp8_e32 v[52:53], v118
	v_cvt_pk_f32_fp8_sdwa v[54:55], v118 src0_sel:WORD_1
	v_cvt_pk_f32_fp8_e32 v[56:57], v119
	v_cvt_pk_f32_fp8_sdwa v[58:59], v119 src0_sel:WORD_1
	v_cvt_pk_f32_fp8_e32 v[66:67], v120
	v_cvt_pk_f32_fp8_sdwa v[68:69], v120 src0_sel:WORD_1
	v_cvt_pk_f32_fp8_e32 v[70:71], v121
	v_cvt_pk_f32_fp8_sdwa v[72:73], v121 src0_sel:WORD_1
	v_cvt_pk_f32_fp8_e32 v[74:75], v122
	v_cvt_pk_f32_fp8_sdwa v[76:77], v122 src0_sel:WORD_1
	v_cvt_pk_f32_fp8_e32 v[78:79], v123
	v_cvt_pk_f32_fp8_sdwa v[80:81], v123 src0_sel:WORD_1
	v_pk_mul_f32 v[82:83], v[44:45], v[28:29]
	v_pk_mul_f32 v[86:87], v[66:67], v[28:29]
	v_pk_mul_f32 v[84:85], v[46:47], v[30:31]
	v_pk_mul_f32 v[88:89], v[68:69], v[30:31]
	v_pk_fma_f32 v[82:83], v[48:49], v[32:33], v[82:83]
	v_pk_fma_f32 v[86:87], v[70:71], v[32:33], v[86:87]
	v_pk_fma_f32 v[84:85], v[50:51], v[34:35], v[84:85]
	v_pk_fma_f32 v[88:89], v[72:73], v[34:35], v[88:89]
	v_pk_fma_f32 v[82:83], v[52:53], v[36:37], v[82:83]
	v_pk_fma_f32 v[86:87], v[74:75], v[36:37], v[86:87]
	v_pk_fma_f32 v[84:85], v[54:55], v[38:39], v[84:85]
	v_pk_fma_f32 v[88:89], v[76:77], v[38:39], v[88:89]
	v_pk_fma_f32 v[82:83], v[56:57], v[40:41], v[82:83]
	v_pk_fma_f32 v[86:87], v[78:79], v[40:41], v[86:87]
	v_pk_fma_f32 v[84:85], v[58:59], v[42:43], v[84:85]
	v_pk_fma_f32 v[88:89], v[80:81], v[42:43], v[88:89]
	v_pk_add_f32 v[82:83], v[82:83], v[84:85]
	v_pk_add_f32 v[86:87], v[86:87], v[88:89]
	v_lshl_add_u32 v11, v100, 10, v8
	v_add_f32_e32 v90, v82, v83
	v_add_f32_e32 v94, v86, v87
	global_load_dwordx4 v[116:119], v11, s[6:7]
	v_lshl_add_u32 v65, v101, 10, v8
	v_add_f32_dpp v91, v90, v90 quad_perm:[1,0,3,2] row_mask:0xf bank_mask:0xf
	v_add_f32_dpp v95, v94, v94 quad_perm:[1,0,3,2] row_mask:0xf bank_mask:0xf
	global_load_dwordx4 v[120:123], v65, s[6:7]
	v_add_f32_dpp v92, v91, v91 quad_perm:[2,3,0,1] row_mask:0xf bank_mask:0xf
	v_add_f32_dpp v96, v95, v95 quad_perm:[2,3,0,1] row_mask:0xf bank_mask:0xf
	s_nop 0
	v_add_f32_dpp v93, v92, v92 row_half_mirror row_mask:0xf bank_mask:0xf
	v_add_f32_dpp v97, v96, v96 row_half_mirror row_mask:0xf bank_mask:0xf
	v_fmac_f32_e32 v98, v93, v12
	v_fmac_f32_e32 v98, v97, v13
	s_waitcnt vmcnt(32)
	v_cvt_pk_f32_fp8_e32 v[44:45], v124
	v_cvt_pk_f32_fp8_sdwa v[46:47], v124 src0_sel:WORD_1
	v_cvt_pk_f32_fp8_e32 v[48:49], v125
	v_cvt_pk_f32_fp8_sdwa v[50:51], v125 src0_sel:WORD_1
	v_cvt_pk_f32_fp8_e32 v[52:53], v126
	v_cvt_pk_f32_fp8_sdwa v[54:55], v126 src0_sel:WORD_1
	v_cvt_pk_f32_fp8_e32 v[56:57], v127
	v_cvt_pk_f32_fp8_sdwa v[58:59], v127 src0_sel:WORD_1
	v_cvt_pk_f32_fp8_e32 v[66:67], v128
	v_cvt_pk_f32_fp8_sdwa v[68:69], v128 src0_sel:WORD_1
	v_cvt_pk_f32_fp8_e32 v[70:71], v129
	v_cvt_pk_f32_fp8_sdwa v[72:73], v129 src0_sel:WORD_1
	v_cvt_pk_f32_fp8_e32 v[74:75], v130
	v_cvt_pk_f32_fp8_sdwa v[76:77], v130 src0_sel:WORD_1
	v_cvt_pk_f32_fp8_e32 v[78:79], v131
	v_cvt_pk_f32_fp8_sdwa v[80:81], v131 src0_sel:WORD_1
	v_pk_mul_f32 v[82:83], v[44:45], v[28:29]
	v_pk_mul_f32 v[86:87], v[66:67], v[28:29]
	v_pk_mul_f32 v[84:85], v[46:47], v[30:31]
	v_pk_mul_f32 v[88:89], v[68:69], v[30:31]
	v_pk_fma_f32 v[82:83], v[48:49], v[32:33], v[82:83]
	v_pk_fma_f32 v[86:87], v[70:71], v[32:33], v[86:87]
	v_pk_fma_f32 v[84:85], v[50:51], v[34:35], v[84:85]
	v_pk_fma_f32 v[88:89], v[72:73], v[34:35], v[88:89]
	v_pk_fma_f32 v[82:83], v[52:53], v[36:37], v[82:83]
	v_pk_fma_f32 v[86:87], v[74:75], v[36:37], v[86:87]
	v_pk_fma_f32 v[84:85], v[54:55], v[38:39], v[84:85]
	v_pk_fma_f32 v[88:89], v[76:77], v[38:39], v[88:89]
	v_pk_fma_f32 v[82:83], v[56:57], v[40:41], v[82:83]
	v_pk_fma_f32 v[86:87], v[78:79], v[40:41], v[86:87]
	v_pk_fma_f32 v[84:85], v[58:59], v[42:43], v[84:85]
	v_pk_fma_f32 v[88:89], v[80:81], v[42:43], v[88:89]
	v_pk_add_f32 v[82:83], v[82:83], v[84:85]
	v_pk_add_f32 v[86:87], v[86:87], v[88:89]
	v_lshl_add_u32 v11, v102, 10, v8
	v_add_f32_e32 v90, v82, v83
	v_add_f32_e32 v94, v86, v87
	global_load_dwordx4 v[124:127], v11, s[6:7]
	v_lshl_add_u32 v65, v103, 10, v8
	v_add_f32_dpp v91, v90, v90 quad_perm:[1,0,3,2] row_mask:0xf bank_mask:0xf
	v_add_f32_dpp v95, v94, v94 quad_perm:[1,0,3,2] row_mask:0xf bank_mask:0xf
	global_load_dwordx4 v[128:131], v65, s[6:7]
	v_add_f32_dpp v92, v91, v91 quad_perm:[2,3,0,1] row_mask:0xf bank_mask:0xf
	v_add_f32_dpp v96, v95, v95 quad_perm:[2,3,0,1] row_mask:0xf bank_mask:0xf
	s_nop 0
	v_add_f32_dpp v93, v92, v92 row_half_mirror row_mask:0xf bank_mask:0xf
	v_add_f32_dpp v97, v96, v96 row_half_mirror row_mask:0xf bank_mask:0xf
	v_fmac_f32_e32 v98, v93, v14
	v_fmac_f32_e32 v98, v97, v15
	s_waitcnt vmcnt(32)
; DI void phase_peer_down(const Params& p) {
;     ...
;       for (int bi = 0; bi < 8; ++bi) {
;         u32x4 dr[8];
; #pragma unroll
;         for (int k = 0; k < 8; ++k) {
;           const int er = __builtin_amdgcn_readlane(ev, bi * 8 + k);
;           dr[k] = *reinterpret_cast<const u32x4*>(exd + (size_t)er * 1024 + lane * 16);
;         }
;         const int pmine = bi * 8 + (lane & 7);
;         const int emine = __shfl(ev, pmine);
;         const float gsel = __shfl(gv, pmine);
;         const float sd = esc[emine];
;         const float su = esc[16384 + emine];
;         float part[8];
; #pragma unroll
;         for (int k = 0; k < 8; ++k) {
;           float a0 = 0.f, a1 = 0.f;
; #pragma unroll
;           for (int w = 0; w < 4; ++w) {
;             f2_t lo = __builtin_amdgcn_cvt_pk_f32_fp8((int)dr[k][w], false);
;             f2_t hi = __builtin_amdgcn_cvt_pk_f32_fp8((int)dr[k][w], true);
;             a0 = fmaf(lo[0], x[4 * w], a0); a1 = fmaf(lo[1], x[4 * w + 1], a1);
;             a0 = fmaf(hi[0], x[4 * w + 2], a0); a1 = fmaf(hi[1], x[4 * w + 3], a1);
;           }
;           part[k] = a0 + a1;
;         }
;         const float r1 = reduce8(part, lane) * sd;
;         const bool mine = (lane >> 3) == bi;
;         racc = mine ? r1 : racc; gacc = mine ? gsel * su : gacc;
;       }
	v_cvt_pk_f32_fp8_e32 v[44:45], v132
	v_cvt_pk_f32_fp8_sdwa v[46:47], v132 src0_sel:WORD_1
	v_cvt_pk_f32_fp8_e32 v[48:49], v133
	v_cvt_pk_f32_fp8_sdwa v[50:51], v133 src0_sel:WORD_1
	v_cvt_pk_f32_fp8_e32 v[52:53], v134
	v_cvt_pk_f32_fp8_sdwa v[54:55], v134 src0_sel:WORD_1
	v_cvt_pk_f32_fp8_e32 v[56:57], v135
	v_cvt_pk_f32_fp8_sdwa v[58:59], v135 src0_sel:WORD_1
	v_cvt_pk_f32_fp8_e32 v[66:67], v136
	v_cvt_pk_f32_fp8_sdwa v[68:69], v136 src0_sel:WORD_1
	v_cvt_pk_f32_fp8_e32 v[70:71], v137
	v_cvt_pk_f32_fp8_sdwa v[72:73], v137 src0_sel:WORD_1
	v_cvt_pk_f32_fp8_e32 v[74:75], v138
	v_cvt_pk_f32_fp8_sdwa v[76:77], v138 src0_sel:WORD_1
	v_cvt_pk_f32_fp8_e32 v[78:79], v139
	v_cvt_pk_f32_fp8_sdwa v[80:81], v139 src0_sel:WORD_1
	v_pk_mul_f32 v[82:83], v[44:45], v[28:29]
	v_pk_mul_f32 v[86:87], v[66:67], v[28:29]
	v_pk_mul_f32 v[84:85], v[46:47], v[30:31]
	v_pk_mul_f32 v[88:89], v[68:69], v[30:31]
	v_pk_fma_f32 v[82:83], v[48:49], v[32:33], v[82:83]
	v_pk_fma_f32 v[86:87], v[70:71], v[32:33], v[86:87]
	v_pk_fma_f32 v[84:85], v[50:51], v[34:35], v[84:85]
	v_pk_fma_f32 v[88:89], v[72:73], v[34:35], v[88:89]
	v_pk_fma_f32 v[82:83], v[52:53], v[36:37], v[82:83]
	v_pk_fma_f32 v[86:87], v[74:75], v[36:37], v[86:87]
	v_pk_fma_f32 v[84:85], v[54:55], v[38:39], v[84:85]
	v_pk_fma_f32 v[88:89], v[76:77], v[38:39], v[88:89]
	v_pk_fma_f32 v[82:83], v[56:57], v[40:41], v[82:83]
	v_pk_fma_f32 v[86:87], v[78:79], v[40:41], v[86:87]
	v_pk_fma_f32 v[84:85], v[58:59], v[42:43], v[84:85]
	v_pk_fma_f32 v[88:89], v[80:81], v[42:43], v[88:89]
	v_pk_add_f32 v[82:83], v[82:83], v[84:85]
	v_pk_add_f32 v[86:87], v[86:87], v[88:89]
	v_lshl_add_u32 v11, v104, 10, v8
	v_add_f32_e32 v90, v82, v83
	v_add_f32_e32 v94, v86, v87
	global_load_dwordx4 v[132:135], v11, s[6:7]
	v_lshl_add_u32 v65, v105, 10, v8
	v_add_f32_dpp v91, v90, v90 quad_perm:[1,0,3,2] row_mask:0xf bank_mask:0xf
	v_add_f32_dpp v95, v94, v94 quad_perm:[1,0,3,2] row_mask:0xf bank_mask:0xf
	global_load_dwordx4 v[136:139], v65, s[6:7]
	v_add_f32_dpp v92, v91, v91 quad_perm:[2,3,0,1] row_mask:0xf bank_mask:0xf
	v_add_f32_dpp v96, v95, v95 quad_perm:[2,3,0,1] row_mask:0xf bank_mask:0xf
	s_nop 0
	v_add_f32_dpp v93, v92, v92 row_half_mirror row_mask:0xf bank_mask:0xf
	v_add_f32_dpp v97, v96, v96 row_half_mirror row_mask:0xf bank_mask:0xf
	v_fmac_f32_e32 v98, v93, v16
	v_fmac_f32_e32 v98, v97, v17
	s_waitcnt vmcnt(32)
	v_cvt_pk_f32_fp8_e32 v[44:45], v140
	v_cvt_pk_f32_fp8_sdwa v[46:47], v140 src0_sel:WORD_1
	v_cvt_pk_f32_fp8_e32 v[48:49], v141
	v_cvt_pk_f32_fp8_sdwa v[50:51], v141 src0_sel:WORD_1
	v_cvt_pk_f32_fp8_e32 v[52:53], v142
	v_cvt_pk_f32_fp8_sdwa v[54:55], v142 src0_sel:WORD_1
	v_cvt_pk_f32_fp8_e32 v[56:57], v143
	v_cvt_pk_f32_fp8_sdwa v[58:59], v143 src0_sel:WORD_1
	v_cvt_pk_f32_fp8_e32 v[66:67], v144
	v_cvt_pk_f32_fp8_sdwa v[68:69], v144 src0_sel:WORD_1
	v_cvt_pk_f32_fp8_e32 v[70:71], v145
	v_cvt_pk_f32_fp8_sdwa v[72:73], v145 src0_sel:WORD_1
	v_cvt_pk_f32_fp8_e32 v[74:75], v146
	v_cvt_pk_f32_fp8_sdwa v[76:77], v146 src0_sel:WORD_1
	v_cvt_pk_f32_fp8_e32 v[78:79], v147
	v_cvt_pk_f32_fp8_sdwa v[80:81], v147 src0_sel:WORD_1
	v_pk_mul_f32 v[82:83], v[44:45], v[28:29]
	v_pk_mul_f32 v[86:87], v[66:67], v[28:29]
	v_pk_mul_f32 v[84:85], v[46:47], v[30:31]
	v_pk_mul_f32 v[88:89], v[68:69], v[30:31]
	v_pk_fma_f32 v[82:83], v[48:49], v[32:33], v[82:83]
	v_pk_fma_f32 v[86:87], v[70:71], v[32:33], v[86:87]
	v_pk_fma_f32 v[84:85], v[50:51], v[34:35], v[84:85]
	v_pk_fma_f32 v[88:89], v[72:73], v[34:35], v[88:89]
	v_pk_fma_f32 v[82:83], v[52:53], v[36:37], v[82:83]
	v_pk_fma_f32 v[86:87], v[74:75], v[36:37], v[86:87]
	v_pk_fma_f32 v[84:85], v[54:55], v[38:39], v[84:85]
	v_pk_fma_f32 v[88:89], v[76:77], v[38:39], v[88:89]
	v_pk_fma_f32 v[82:83], v[56:57], v[40:41], v[82:83]
	v_pk_fma_f32 v[86:87], v[78:79], v[40:41], v[86:87]
	v_pk_fma_f32 v[84:85], v[58:59], v[42:43], v[84:85]
	v_pk_fma_f32 v[88:89], v[80:81], v[42:43], v[88:89]
	v_pk_add_f32 v[82:83], v[82:83], v[84:85]
	v_pk_add_f32 v[86:87], v[86:87], v[88:89]
	v_lshl_add_u32 v11, v106, 10, v8
	v_add_f32_e32 v90, v82, v83
	v_add_f32_e32 v94, v86, v87
	global_load_dwordx4 v[140:143], v11, s[6:7]
	v_lshl_add_u32 v65, v107, 10, v8
	v_add_f32_dpp v91, v90, v90 quad_perm:[1,0,3,2] row_mask:0xf bank_mask:0xf
	v_add_f32_dpp v95, v94, v94 quad_perm:[1,0,3,2] row_mask:0xf bank_mask:0xf
	global_load_dwordx4 v[144:147], v65, s[6:7]
	v_add_f32_dpp v92, v91, v91 quad_perm:[2,3,0,1] row_mask:0xf bank_mask:0xf
	v_add_f32_dpp v96, v95, v95 quad_perm:[2,3,0,1] row_mask:0xf bank_mask:0xf
	s_nop 0
	v_add_f32_dpp v93, v92, v92 row_half_mirror row_mask:0xf bank_mask:0xf
	v_add_f32_dpp v97, v96, v96 row_half_mirror row_mask:0xf bank_mask:0xf
	v_fmac_f32_e32 v98, v93, v18
	v_fmac_f32_e32 v98, v97, v19
	s_waitcnt vmcnt(32)
; DI void phase_peer_down(const Params& p) {
;     ...
;       for (int bi = 0; bi < 8; ++bi) {
;         u32x4 dr[8];
; #pragma unroll
;         for (int k = 0; k < 8; ++k) {
;           const int er = __builtin_amdgcn_readlane(ev, bi * 8 + k);
;           dr[k] = *reinterpret_cast<const u32x4*>(exd + (size_t)er * 1024 + lane * 16);
;         }
;         const int pmine = bi * 8 + (lane & 7);
;         const int emine = __shfl(ev, pmine);
;         const float gsel = __shfl(gv, pmine);
;         const float sd = esc[emine];
;         const float su = esc[16384 + emine];
;         float part[8];
; #pragma unroll
;         for (int k = 0; k < 8; ++k) {
;           float a0 = 0.f, a1 = 0.f;
; #pragma unroll
;           for (int w = 0; w < 4; ++w) {
;             f2_t lo = __builtin_amdgcn_cvt_pk_f32_fp8((int)dr[k][w], false);
;             f2_t hi = __builtin_amdgcn_cvt_pk_f32_fp8((int)dr[k][w], true);
;             a0 = fmaf(lo[0], x[4 * w], a0); a1 = fmaf(lo[1], x[4 * w + 1], a1);
;             a0 = fmaf(hi[0], x[4 * w + 2], a0); a1 = fmaf(hi[1], x[4 * w + 3], a1);
;           }
;           part[k] = a0 + a1;
;         }
;         const float r1 = reduce8(part, lane) * sd;
;         const bool mine = (lane >> 3) == bi;
;         racc = mine ? r1 : racc; gacc = mine ? gsel * su : gacc;
;       }
	v_cvt_pk_f32_fp8_e32 v[44:45], v180
	v_cvt_pk_f32_fp8_sdwa v[46:47], v180 src0_sel:WORD_1
	v_cvt_pk_f32_fp8_e32 v[48:49], v181
	v_cvt_pk_f32_fp8_sdwa v[50:51], v181 src0_sel:WORD_1
	v_cvt_pk_f32_fp8_e32 v[52:53], v182
	v_cvt_pk_f32_fp8_sdwa v[54:55], v182 src0_sel:WORD_1
	v_cvt_pk_f32_fp8_e32 v[56:57], v183
	v_cvt_pk_f32_fp8_sdwa v[58:59], v183 src0_sel:WORD_1
	v_cvt_pk_f32_fp8_e32 v[66:67], v184
	v_cvt_pk_f32_fp8_sdwa v[68:69], v184 src0_sel:WORD_1
	v_cvt_pk_f32_fp8_e32 v[70:71], v185
	v_cvt_pk_f32_fp8_sdwa v[72:73], v185 src0_sel:WORD_1
	v_cvt_pk_f32_fp8_e32 v[74:75], v186
	v_cvt_pk_f32_fp8_sdwa v[76:77], v186 src0_sel:WORD_1
	v_cvt_pk_f32_fp8_e32 v[78:79], v187
	v_cvt_pk_f32_fp8_sdwa v[80:81], v187 src0_sel:WORD_1
	v_pk_mul_f32 v[82:83], v[44:45], v[28:29]
	v_pk_mul_f32 v[86:87], v[66:67], v[28:29]
	v_pk_mul_f32 v[84:85], v[46:47], v[30:31]
	v_pk_mul_f32 v[88:89], v[68:69], v[30:31]
	v_pk_fma_f32 v[82:83], v[48:49], v[32:33], v[82:83]
	v_pk_fma_f32 v[86:87], v[70:71], v[32:33], v[86:87]
	v_pk_fma_f32 v[84:85], v[50:51], v[34:35], v[84:85]
	v_pk_fma_f32 v[88:89], v[72:73], v[34:35], v[88:89]
	v_pk_fma_f32 v[82:83], v[52:53], v[36:37], v[82:83]
	v_pk_fma_f32 v[86:87], v[74:75], v[36:37], v[86:87]
	v_pk_fma_f32 v[84:85], v[54:55], v[38:39], v[84:85]
	v_pk_fma_f32 v[88:89], v[76:77], v[38:39], v[88:89]
	v_pk_fma_f32 v[82:83], v[56:57], v[40:41], v[82:83]
	v_pk_fma_f32 v[86:87], v[78:79], v[40:41], v[86:87]
	v_pk_fma_f32 v[84:85], v[58:59], v[42:43], v[84:85]
	v_pk_fma_f32 v[88:89], v[80:81], v[42:43], v[88:89]
	v_pk_add_f32 v[82:83], v[82:83], v[84:85]
	v_pk_add_f32 v[86:87], v[86:87], v[88:89]
	v_lshl_add_u32 v11, v108, 10, v8
	v_add_f32_e32 v90, v82, v83
	v_add_f32_e32 v94, v86, v87
	global_load_dwordx4 v[180:183], v11, s[6:7]
	v_lshl_add_u32 v65, v109, 10, v8
	v_add_f32_dpp v91, v90, v90 quad_perm:[1,0,3,2] row_mask:0xf bank_mask:0xf
	v_add_f32_dpp v95, v94, v94 quad_perm:[1,0,3,2] row_mask:0xf bank_mask:0xf
	global_load_dwordx4 v[184:187], v65, s[6:7]
	v_add_f32_dpp v92, v91, v91 quad_perm:[2,3,0,1] row_mask:0xf bank_mask:0xf
	v_add_f32_dpp v96, v95, v95 quad_perm:[2,3,0,1] row_mask:0xf bank_mask:0xf
	s_nop 0
	v_add_f32_dpp v93, v92, v92 row_half_mirror row_mask:0xf bank_mask:0xf
	v_add_f32_dpp v97, v96, v96 row_half_mirror row_mask:0xf bank_mask:0xf
	v_fmac_f32_e32 v99, v93, v12
	v_fmac_f32_e32 v99, v97, v13
	s_waitcnt vmcnt(32)
	v_cvt_pk_f32_fp8_e32 v[44:45], v188
	v_cvt_pk_f32_fp8_sdwa v[46:47], v188 src0_sel:WORD_1
	v_cvt_pk_f32_fp8_e32 v[48:49], v189
	v_cvt_pk_f32_fp8_sdwa v[50:51], v189 src0_sel:WORD_1
	v_cvt_pk_f32_fp8_e32 v[52:53], v190
	v_cvt_pk_f32_fp8_sdwa v[54:55], v190 src0_sel:WORD_1
	v_cvt_pk_f32_fp8_e32 v[56:57], v191
	v_cvt_pk_f32_fp8_sdwa v[58:59], v191 src0_sel:WORD_1
	v_cvt_pk_f32_fp8_e32 v[66:67], v192
	v_cvt_pk_f32_fp8_sdwa v[68:69], v192 src0_sel:WORD_1
	v_cvt_pk_f32_fp8_e32 v[70:71], v193
	v_cvt_pk_f32_fp8_sdwa v[72:73], v193 src0_sel:WORD_1
	v_cvt_pk_f32_fp8_e32 v[74:75], v194
	v_cvt_pk_f32_fp8_sdwa v[76:77], v194 src0_sel:WORD_1
	v_cvt_pk_f32_fp8_e32 v[78:79], v195
	v_cvt_pk_f32_fp8_sdwa v[80:81], v195 src0_sel:WORD_1
	v_pk_mul_f32 v[82:83], v[44:45], v[28:29]
	v_pk_mul_f32 v[86:87], v[66:67], v[28:29]
	v_pk_mul_f32 v[84:85], v[46:47], v[30:31]
	v_pk_mul_f32 v[88:89], v[68:69], v[30:31]
	v_pk_fma_f32 v[82:83], v[48:49], v[32:33], v[82:83]
	v_pk_fma_f32 v[86:87], v[70:71], v[32:33], v[86:87]
	v_pk_fma_f32 v[84:85], v[50:51], v[34:35], v[84:85]
	v_pk_fma_f32 v[88:89], v[72:73], v[34:35], v[88:89]
	v_pk_fma_f32 v[82:83], v[52:53], v[36:37], v[82:83]
	v_pk_fma_f32 v[86:87], v[74:75], v[36:37], v[86:87]
	v_pk_fma_f32 v[84:85], v[54:55], v[38:39], v[84:85]
	v_pk_fma_f32 v[88:89], v[76:77], v[38:39], v[88:89]
	v_pk_fma_f32 v[82:83], v[56:57], v[40:41], v[82:83]
	v_pk_fma_f32 v[86:87], v[78:79], v[40:41], v[86:87]
	v_pk_fma_f32 v[84:85], v[58:59], v[42:43], v[84:85]
	v_pk_fma_f32 v[88:89], v[80:81], v[42:43], v[88:89]
	v_pk_add_f32 v[82:83], v[82:83], v[84:85]
	v_pk_add_f32 v[86:87], v[86:87], v[88:89]
	v_lshl_add_u32 v11, v110, 10, v8
	v_add_f32_e32 v90, v82, v83
	v_add_f32_e32 v94, v86, v87
	global_load_dwordx4 v[188:191], v11, s[6:7]
	v_lshl_add_u32 v65, v111, 10, v8
	v_add_f32_dpp v91, v90, v90 quad_perm:[1,0,3,2] row_mask:0xf bank_mask:0xf
	v_add_f32_dpp v95, v94, v94 quad_perm:[1,0,3,2] row_mask:0xf bank_mask:0xf
	global_load_dwordx4 v[192:195], v65, s[6:7]
	v_add_f32_dpp v92, v91, v91 quad_perm:[2,3,0,1] row_mask:0xf bank_mask:0xf
	v_add_f32_dpp v96, v95, v95 quad_perm:[2,3,0,1] row_mask:0xf bank_mask:0xf
	s_nop 0
	v_add_f32_dpp v93, v92, v92 row_half_mirror row_mask:0xf bank_mask:0xf
	v_add_f32_dpp v97, v96, v96 row_half_mirror row_mask:0xf bank_mask:0xf
	v_fmac_f32_e32 v99, v93, v14
	v_fmac_f32_e32 v99, v97, v15
	s_waitcnt vmcnt(32)
; DI void phase_peer_down(const Params& p) {
;     ...
;       for (int bi = 0; bi < 8; ++bi) {
;         u32x4 dr[8];
; #pragma unroll
;         for (int k = 0; k < 8; ++k) {
;           const int er = __builtin_amdgcn_readlane(ev, bi * 8 + k);
;           dr[k] = *reinterpret_cast<const u32x4*>(exd + (size_t)er * 1024 + lane * 16);
;         }
;         const int pmine = bi * 8 + (lane & 7);
;         const int emine = __shfl(ev, pmine);
;         const float gsel = __shfl(gv, pmine);
;         const float sd = esc[emine];
;         const float su = esc[16384 + emine];
;         float part[8];
; #pragma unroll
;         for (int k = 0; k < 8; ++k) {
;           float a0 = 0.f, a1 = 0.f;
; #pragma unroll
;           for (int w = 0; w < 4; ++w) {
;             f2_t lo = __builtin_amdgcn_cvt_pk_f32_fp8((int)dr[k][w], false);
;             f2_t hi = __builtin_amdgcn_cvt_pk_f32_fp8((int)dr[k][w], true);
;             a0 = fmaf(lo[0], x[4 * w], a0); a1 = fmaf(lo[1], x[4 * w + 1], a1);
;             a0 = fmaf(hi[0], x[4 * w + 2], a0); a1 = fmaf(hi[1], x[4 * w + 3], a1);
;           }
;           part[k] = a0 + a1;
;         }
;         const float r1 = reduce8(part, lane) * sd;
;         const bool mine = (lane >> 3) == bi;
;         racc = mine ? r1 : racc; gacc = mine ? gsel * su : gacc;
;       }
;       const float act = 0.5f * racc * (1.f + erff(racc * 0.70710678118654752f));
;       coefw[slot] = gacc * act;
	v_cvt_pk_f32_fp8_e32 v[44:45], v196
	v_cvt_pk_f32_fp8_sdwa v[46:47], v196 src0_sel:WORD_1
	v_cvt_pk_f32_fp8_e32 v[48:49], v197
	v_cvt_pk_f32_fp8_sdwa v[50:51], v197 src0_sel:WORD_1
	v_cvt_pk_f32_fp8_e32 v[52:53], v198
	v_cvt_pk_f32_fp8_sdwa v[54:55], v198 src0_sel:WORD_1
	v_cvt_pk_f32_fp8_e32 v[56:57], v199
	v_cvt_pk_f32_fp8_sdwa v[58:59], v199 src0_sel:WORD_1
	v_cvt_pk_f32_fp8_e32 v[66:67], v200
	v_cvt_pk_f32_fp8_sdwa v[68:69], v200 src0_sel:WORD_1
	v_cvt_pk_f32_fp8_e32 v[70:71], v201
	v_cvt_pk_f32_fp8_sdwa v[72:73], v201 src0_sel:WORD_1
	v_cvt_pk_f32_fp8_e32 v[74:75], v202
	v_cvt_pk_f32_fp8_sdwa v[76:77], v202 src0_sel:WORD_1
	v_cvt_pk_f32_fp8_e32 v[78:79], v203
	v_cvt_pk_f32_fp8_sdwa v[80:81], v203 src0_sel:WORD_1
	v_pk_mul_f32 v[82:83], v[44:45], v[28:29]
	v_pk_mul_f32 v[86:87], v[66:67], v[28:29]
	v_pk_mul_f32 v[84:85], v[46:47], v[30:31]
	v_pk_mul_f32 v[88:89], v[68:69], v[30:31]
	v_pk_fma_f32 v[82:83], v[48:49], v[32:33], v[82:83]
	v_pk_fma_f32 v[86:87], v[70:71], v[32:33], v[86:87]
	v_pk_fma_f32 v[84:85], v[50:51], v[34:35], v[84:85]
	v_pk_fma_f32 v[88:89], v[72:73], v[34:35], v[88:89]
	v_pk_fma_f32 v[82:83], v[52:53], v[36:37], v[82:83]
	v_pk_fma_f32 v[86:87], v[74:75], v[36:37], v[86:87]
	v_pk_fma_f32 v[84:85], v[54:55], v[38:39], v[84:85]
	v_pk_fma_f32 v[88:89], v[76:77], v[38:39], v[88:89]
	v_pk_fma_f32 v[82:83], v[56:57], v[40:41], v[82:83]
	v_pk_fma_f32 v[86:87], v[78:79], v[40:41], v[86:87]
	v_pk_fma_f32 v[84:85], v[58:59], v[42:43], v[84:85]
	v_pk_fma_f32 v[88:89], v[80:81], v[42:43], v[88:89]
	v_pk_add_f32 v[82:83], v[82:83], v[84:85]
	v_pk_add_f32 v[86:87], v[86:87], v[88:89]
	v_lshl_add_u32 v11, v112, 10, v8
	v_add_f32_e32 v90, v82, v83
	v_add_f32_e32 v94, v86, v87
	global_load_dwordx4 v[196:199], v11, s[6:7]
	v_lshl_add_u32 v65, v113, 10, v8
	v_add_f32_dpp v91, v90, v90 quad_perm:[1,0,3,2] row_mask:0xf bank_mask:0xf
	v_add_f32_dpp v95, v94, v94 quad_perm:[1,0,3,2] row_mask:0xf bank_mask:0xf
	global_load_dwordx4 v[200:203], v65, s[6:7]
	v_add_f32_dpp v92, v91, v91 quad_perm:[2,3,0,1] row_mask:0xf bank_mask:0xf
	v_add_f32_dpp v96, v95, v95 quad_perm:[2,3,0,1] row_mask:0xf bank_mask:0xf
	s_nop 0
	v_add_f32_dpp v93, v92, v92 row_half_mirror row_mask:0xf bank_mask:0xf
	v_add_f32_dpp v97, v96, v96 row_half_mirror row_mask:0xf bank_mask:0xf
	v_fmac_f32_e32 v99, v93, v16
	v_fmac_f32_e32 v99, v97, v17
	s_waitcnt vmcnt(32)
	v_cvt_pk_f32_fp8_e32 v[44:45], v204
	v_cvt_pk_f32_fp8_sdwa v[46:47], v204 src0_sel:WORD_1
	v_cvt_pk_f32_fp8_e32 v[48:49], v205
	v_cvt_pk_f32_fp8_sdwa v[50:51], v205 src0_sel:WORD_1
	v_cvt_pk_f32_fp8_e32 v[52:53], v206
	v_cvt_pk_f32_fp8_sdwa v[54:55], v206 src0_sel:WORD_1
	v_cvt_pk_f32_fp8_e32 v[56:57], v207
	v_cvt_pk_f32_fp8_sdwa v[58:59], v207 src0_sel:WORD_1
	v_cvt_pk_f32_fp8_e32 v[66:67], v208
	v_cvt_pk_f32_fp8_sdwa v[68:69], v208 src0_sel:WORD_1
	v_cvt_pk_f32_fp8_e32 v[70:71], v209
	v_cvt_pk_f32_fp8_sdwa v[72:73], v209 src0_sel:WORD_1
	v_cvt_pk_f32_fp8_e32 v[74:75], v210
	v_cvt_pk_f32_fp8_sdwa v[76:77], v210 src0_sel:WORD_1
	v_cvt_pk_f32_fp8_e32 v[78:79], v211
	v_cvt_pk_f32_fp8_sdwa v[80:81], v211 src0_sel:WORD_1
	v_pk_mul_f32 v[82:83], v[44:45], v[28:29]
	v_pk_mul_f32 v[86:87], v[66:67], v[28:29]
	v_pk_mul_f32 v[84:85], v[46:47], v[30:31]
	v_pk_mul_f32 v[88:89], v[68:69], v[30:31]
	v_pk_fma_f32 v[82:83], v[48:49], v[32:33], v[82:83]
	v_pk_fma_f32 v[86:87], v[70:71], v[32:33], v[86:87]
	v_pk_fma_f32 v[84:85], v[50:51], v[34:35], v[84:85]
	v_pk_fma_f32 v[88:89], v[72:73], v[34:35], v[88:89]
	v_pk_fma_f32 v[82:83], v[52:53], v[36:37], v[82:83]
	v_pk_fma_f32 v[86:87], v[74:75], v[36:37], v[86:87]
	v_pk_fma_f32 v[84:85], v[54:55], v[38:39], v[84:85]
	v_pk_fma_f32 v[88:89], v[76:77], v[38:39], v[88:89]
	v_pk_fma_f32 v[82:83], v[56:57], v[40:41], v[82:83]
	v_pk_fma_f32 v[86:87], v[78:79], v[40:41], v[86:87]
	v_pk_fma_f32 v[84:85], v[58:59], v[42:43], v[84:85]
	v_pk_fma_f32 v[88:89], v[80:81], v[42:43], v[88:89]
	v_pk_add_f32 v[82:83], v[82:83], v[84:85]
	v_pk_add_f32 v[86:87], v[86:87], v[88:89]
	v_lshl_add_u32 v11, v114, 10, v8
	v_add_f32_e32 v90, v82, v83
	v_add_f32_e32 v94, v86, v87
	global_load_dwordx4 v[204:207], v11, s[6:7]
	v_lshl_add_u32 v65, v115, 10, v8
	v_add_f32_dpp v91, v90, v90 quad_perm:[1,0,3,2] row_mask:0xf bank_mask:0xf
	v_add_f32_dpp v95, v94, v94 quad_perm:[1,0,3,2] row_mask:0xf bank_mask:0xf
	global_load_dwordx4 v[208:211], v65, s[6:7]
	v_add_f32_dpp v92, v91, v91 quad_perm:[2,3,0,1] row_mask:0xf bank_mask:0xf
	v_add_f32_dpp v96, v95, v95 quad_perm:[2,3,0,1] row_mask:0xf bank_mask:0xf
	s_nop 0
	v_add_f32_dpp v93, v92, v92 row_half_mirror row_mask:0xf bank_mask:0xf
	v_add_f32_dpp v97, v96, v96 row_half_mirror row_mask:0xf bank_mask:0xf
	v_fmac_f32_e32 v99, v93, v18
	v_fmac_f32_e32 v99, v97, v19
	ds_write_b64 v10, v[98:99]
	s_add_i32 s18, s18, 1
	s_cmpk_lt_u32 s18, 0x80
	s_cbranch_scc1 .Lpd_loop
	s_waitcnt vmcnt(0) lgkmcnt(0)
	v_lshl_add_u32 v3, v2, 1, v1
	s_mov_b32 s18, 0
	s_mov_b32 s25, 0x378e98ab
	s_mov_b32 s26, 0x3b7cd369
	s_mov_b32 s27, 0xbcc618b2
	s_mov_b32 s28, 0x3dda74e4
	s_mov_b32 s29, 0x3f228afd
	s_mov_b32 s30, 0x3e03c728
	s_mov_b32 s31, 0xbfb8aa3b
	s_mov_b32 s36, 0x42ce8ed0
	s_mov_b32 s37, 0xc2b17218
	s_brev_b32 s38, -2
	v_mov_b32_e32 v90, 0x3ba10414
	v_mov_b32_e32 v91, 0xb9c68948
	v_mov_b32_e32 v92, 0x7f800000
; DI void phase_peer_down(const Params& p) {
;     ...
;       const size_t slot = (size_t)tok * 128 + half * 64 + lane;
;       const int ev = eidx[slot];
;       const float gv = gate[slot];
;       float racc = 0.f, gacc = 0.f;
; #pragma unroll 1
;       for (int bi = 0; bi < 8; ++bi) {
;         u32x4 dr[8];
; #pragma unroll
;         for (int k = 0; k < 8; ++k) {
;           const int er = __builtin_amdgcn_readlane(ev, bi * 8 + k);
;           dr[k] = *reinterpret_cast<const u32x4*>(exd + (size_t)er * 1024 + lane * 16);
;         }
;         const int pmine = bi * 8 + (lane & 7);
;         const int emine = __shfl(ev, pmine);
;         const float gsel = __shfl(gv, pmine);
;         const float sd = esc[emine];
;         const float su = esc[16384 + emine];
;         float part[8];
; #pragma unroll
;         for (int k = 0; k < 8; ++k) {
;           float a0 = 0.f, a1 = 0.f;
; #pragma unroll
;           for (int w = 0; w < 4; ++w) {
;             f2_t lo = __builtin_amdgcn_cvt_pk_f32_fp8((int)dr[k][w], false);
;             f2_t hi = __builtin_amdgcn_cvt_pk_f32_fp8((int)dr[k][w], true);
;             a0 = fmaf(lo[0], x[4 * w], a0); a1 = fmaf(lo[1], x[4 * w + 1], a1);
;             a0 = fmaf(hi[0], x[4 * w + 2], a0); a1 = fmaf(hi[1], x[4 * w + 3], a1);
;           }
;           part[k] = a0 + a1;
;         }
;         const float r1 = reduce8(part, lane) * sd;
;         const bool mine = (lane >> 3) == bi;
;         racc = mine ? r1 : racc; gacc = mine ? gsel * su : gacc;
;       }
;       const float act = 0.5f * racc * (1.f + erff(racc * 0.70710678118654752f));
;       coefw[slot] = gacc * act;
.Lpd_epi:
	s_add_i32 s20, s18, 0
	s_lshl_b32 s21, s20, 11
	s_lshl_b32 s22, s20, 9
	v_add_u32_e32 v11, s21, v64
	v_lshl_add_u32 v116, v11, 9, v3
	v_add_u32_e32 v10, s22, v4
	ds_read_b64 v[100:101], v10
	global_load_dword v20, v116, s[4:5]
	global_load_dword v28, v116, s[4:5] offset:256
	global_load_dword v36, v116, s[14:15]
	global_load_dword v44, v116, s[14:15] offset:256
	s_add_i32 s20, s18, 1
	s_lshl_b32 s21, s20, 11
	s_lshl_b32 s22, s20, 9
	v_add_u32_e32 v11, s21, v64
	v_lshl_add_u32 v117, v11, 9, v3
	v_add_u32_e32 v10, s22, v4
	ds_read_b64 v[102:103], v10
	global_load_dword v21, v117, s[4:5]
	global_load_dword v29, v117, s[4:5] offset:256
	global_load_dword v37, v117, s[14:15]
	global_load_dword v45, v117, s[14:15] offset:256
	s_add_i32 s20, s18, 2
	s_lshl_b32 s21, s20, 11
	s_lshl_b32 s22, s20, 9
	v_add_u32_e32 v11, s21, v64
	v_lshl_add_u32 v118, v11, 9, v3
	v_add_u32_e32 v10, s22, v4
	ds_read_b64 v[104:105], v10
	global_load_dword v22, v118, s[4:5]
	global_load_dword v30, v118, s[4:5] offset:256
	global_load_dword v38, v118, s[14:15]
	global_load_dword v46, v118, s[14:15] offset:256
	s_add_i32 s20, s18, 3
	s_lshl_b32 s21, s20, 11
	s_lshl_b32 s22, s20, 9
	v_add_u32_e32 v11, s21, v64
	v_lshl_add_u32 v119, v11, 9, v3
	v_add_u32_e32 v10, s22, v4
	ds_read_b64 v[106:107], v10
	global_load_dword v23, v119, s[4:5]
	global_load_dword v31, v119, s[4:5] offset:256
	global_load_dword v39, v119, s[14:15]
	global_load_dword v47, v119, s[14:15] offset:256
	s_add_i32 s20, s18, 4
	s_lshl_b32 s21, s20, 11
	s_lshl_b32 s22, s20, 9
	v_add_u32_e32 v11, s21, v64
	v_lshl_add_u32 v120, v11, 9, v3
	v_add_u32_e32 v10, s22, v4
	ds_read_b64 v[108:109], v10
	global_load_dword v24, v120, s[4:5]
	global_load_dword v32, v120, s[4:5] offset:256
	global_load_dword v40, v120, s[14:15]
	global_load_dword v48, v120, s[14:15] offset:256
	s_add_i32 s20, s18, 5
	s_lshl_b32 s21, s20, 11
	s_lshl_b32 s22, s20, 9
	v_add_u32_e32 v11, s21, v64
	v_lshl_add_u32 v121, v11, 9, v3
	v_add_u32_e32 v10, s22, v4
	ds_read_b64 v[110:111], v10
	global_load_dword v25, v121, s[4:5]
	global_load_dword v33, v121, s[4:5] offset:256
	global_load_dword v41, v121, s[14:15]
	global_load_dword v49, v121, s[14:15] offset:256
	s_add_i32 s20, s18, 6
	s_lshl_b32 s21, s20, 11
	s_lshl_b32 s22, s20, 9
	v_add_u32_e32 v11, s21, v64
	v_lshl_add_u32 v122, v11, 9, v3
	v_add_u32_e32 v10, s22, v4
	ds_read_b64 v[112:113], v10
	global_load_dword v26, v122, s[4:5]
	global_load_dword v34, v122, s[4:5] offset:256
	global_load_dword v42, v122, s[14:15]
	global_load_dword v50, v122, s[14:15] offset:256
	s_add_i32 s20, s18, 7
	s_lshl_b32 s21, s20, 11
	s_lshl_b32 s22, s20, 9
	v_add_u32_e32 v11, s21, v64
	v_lshl_add_u32 v123, v11, 9, v3
	v_add_u32_e32 v10, s22, v4
	ds_read_b64 v[114:115], v10
	global_load_dword v27, v123, s[4:5]
	global_load_dword v35, v123, s[4:5] offset:256
	global_load_dword v43, v123, s[14:15]
	global_load_dword v51, v123, s[14:15] offset:256
	s_waitcnt vmcnt(0)
	v_lshlrev_b32_e32 v20, 2, v20
	v_lshlrev_b32_e32 v28, 2, v28
	global_load_dword v52, v20, s[12:13]
	global_load_dword v66, v28, s[12:13]
	global_load_dword v74, v20, s[34:35]
	global_load_dword v82, v28, s[34:35]
	v_lshlrev_b32_e32 v21, 2, v21
	v_lshlrev_b32_e32 v29, 2, v29
	global_load_dword v53, v21, s[12:13]
	global_load_dword v67, v29, s[12:13]
	global_load_dword v75, v21, s[34:35]
	global_load_dword v83, v29, s[34:35]
	v_lshlrev_b32_e32 v22, 2, v22
	v_lshlrev_b32_e32 v30, 2, v30
	global_load_dword v54, v22, s[12:13]
	global_load_dword v68, v30, s[12:13]
	global_load_dword v76, v22, s[34:35]
	global_load_dword v84, v30, s[34:35]
	v_lshlrev_b32_e32 v23, 2, v23
	v_lshlrev_b32_e32 v31, 2, v31
	global_load_dword v55, v23, s[12:13]
	global_load_dword v69, v31, s[12:13]
	global_load_dword v77, v23, s[34:35]
	global_load_dword v85, v31, s[34:35]
	v_lshlrev_b32_e32 v24, 2, v24
	v_lshlrev_b32_e32 v32, 2, v32
	global_load_dword v56, v24, s[12:13]
	global_load_dword v70, v32, s[12:13]
	global_load_dword v78, v24, s[34:35]
	global_load_dword v86, v32, s[34:35]
	v_lshlrev_b32_e32 v25, 2, v25
	v_lshlrev_b32_e32 v33, 2, v33
	global_load_dword v57, v25, s[12:13]
	global_load_dword v71, v33, s[12:13]
	global_load_dword v79, v25, s[34:35]
	global_load_dword v87, v33, s[34:35]
	v_lshlrev_b32_e32 v26, 2, v26
	v_lshlrev_b32_e32 v34, 2, v34
	global_load_dword v58, v26, s[12:13]
	global_load_dword v72, v34, s[12:13]
	global_load_dword v80, v26, s[34:35]
	global_load_dword v88, v34, s[34:35]
	v_lshlrev_b32_e32 v27, 2, v27
	v_lshlrev_b32_e32 v35, 2, v35
	global_load_dword v59, v27, s[12:13]
	global_load_dword v73, v35, s[12:13]
	global_load_dword v81, v27, s[34:35]
	global_load_dword v89, v35, s[34:35]
	s_waitcnt vmcnt(0) lgkmcnt(0)
	v_mul_f32_e32 v93, v100, v52
	v_mul_f32_e32 v99, v36, v74
	v_mul_f32_e32 v94, 0x3f3504f3, v93
	v_cmp_nlt_f32_e64 s[20:21], |v94|, 1.0
	s_and_saveexec_b64 s[22:23], s[20:21]
	s_xor_b64 s[20:21], exec, s[22:23]
	s_cbranch_execz .Lpd_erf_a1
	v_fma_f32 v95, |v94|, s25, v91
	v_fma_f32 v95, |v94|, v95, s26
	v_fma_f32 v95, |v94|, v95, s27
	v_fma_f32 v95, |v94|, v95, s28
	v_fma_f32 v95, |v94|, v95, s29
	v_fma_f32 v95, |v94|, v95, s30
	v_fma_f32 v95, |v94|, v95, |v94|
	v_mul_f32_e32 v96, 0xbfb8aa3b, v95
	v_fma_f32 v97, v95, s31, -v96
	v_rndne_f32_e32 v98, v96
	v_fmac_f32_e32 v97, 0xb2a5705f, v95
	v_sub_f32_e32 v96, v96, v98
	v_add_f32_e32 v96, v96, v97
	v_cvt_i32_f32_e32 v97, v98
	v_exp_f32_e32 v96, v96
	v_cmp_nlt_f32_e32 vcc, s36, v95
	v_ldexp_f32 v96, v96, v97
	s_nop 0
	v_cndmask_b32_e32 v96, 0, v96, vcc
	v_cmp_ngt_f32_e32 vcc, s37, v95
	s_nop 1
	v_cndmask_b32_e32 v95, v92, v96, vcc
	v_sub_f32_e32 v95, 1.0, v95
; DI void phase_peer_down(const Params& p) {
;     ...
;         const float r1 = reduce8(part, lane) * sd;
;         const bool mine = (lane >> 3) == bi;
;         racc = mine ? r1 : racc; gacc = mine ? gsel * su : gacc;
;       }
;       const float act = 0.5f * racc * (1.f + erff(racc * 0.70710678118654752f));
;       coefw[slot] = gacc * act;
.Lpd_erf_a1:
	s_andn2_saveexec_b64 s[20:21], s[20:21]
	s_cbranch_execz .Lpd_erf_b1
	v_mul_f32_e32 v95, v94, v94
	v_fmamk_f32 v96, v95, 0xba1345e1, v90
	v_fmaak_f32 v96, v95, v96, 0xbcdac9b8
	v_fmaak_f32 v96, v95, v96, 0x3de703be
	v_fmaak_f32 v96, v95, v96, 0xbec09330
	v_fmaak_f32 v95, v95, v96, 0x3e0375d0
	v_fma_f32 v95, |v94|, v95, |v94|
.Lpd_erf_b1:
	s_or_b64 exec, exec, s[20:21]
	v_bfi_b32 v94, s38, v95, v94
	v_mul_f32_e32 v93, 0.5, v93
	v_add_f32_e32 v94, 1.0, v94
	v_mul_f32_e32 v93, v93, v94
	v_mul_f32_e32 v93, v99, v93
	global_store_dword v116, v93, s[16:17]
	v_mul_f32_e32 v93, v101, v66
	v_mul_f32_e32 v99, v44, v82
	v_mul_f32_e32 v94, 0x3f3504f3, v93
	v_cmp_nlt_f32_e64 s[20:21], |v94|, 1.0
	s_and_saveexec_b64 s[22:23], s[20:21]
	s_xor_b64 s[20:21], exec, s[22:23]
	s_cbranch_execz .Lpd_erf_a2
	v_fma_f32 v95, |v94|, s25, v91
	v_fma_f32 v95, |v94|, v95, s26
	v_fma_f32 v95, |v94|, v95, s27
	v_fma_f32 v95, |v94|, v95, s28
	v_fma_f32 v95, |v94|, v95, s29
	v_fma_f32 v95, |v94|, v95, s30
	v_fma_f32 v95, |v94|, v95, |v94|
	v_mul_f32_e32 v96, 0xbfb8aa3b, v95
	v_fma_f32 v97, v95, s31, -v96
	v_rndne_f32_e32 v98, v96
	v_fmac_f32_e32 v97, 0xb2a5705f, v95
	v_sub_f32_e32 v96, v96, v98
	v_add_f32_e32 v96, v96, v97
	v_cvt_i32_f32_e32 v97, v98
	v_exp_f32_e32 v96, v96
	v_cmp_nlt_f32_e32 vcc, s36, v95
	v_ldexp_f32 v96, v96, v97
	s_nop 0
	v_cndmask_b32_e32 v96, 0, v96, vcc
	v_cmp_ngt_f32_e32 vcc, s37, v95
	s_nop 1
	v_cndmask_b32_e32 v95, v92, v96, vcc
	v_sub_f32_e32 v95, 1.0, v95

; DI void phase_peer_down(const Params& p) {
;     ...
;         const float r1 = reduce8(part, lane) * sd;
;         const bool mine = (lane >> 3) == bi;
;         racc = mine ? r1 : racc; gacc = mine ? gsel * su : gacc;
;       }
;       const float act = 0.5f * racc * (1.f + erff(racc * 0.70710678118654752f));
;       coefw[slot] = gacc * act;
.Lpd_erf_b2:
	s_or_b64 exec, exec, s[20:21]
	v_bfi_b32 v94, s38, v95, v94
	v_mul_f32_e32 v93, 0.5, v93
	v_add_f32_e32 v94, 1.0, v94
	v_mul_f32_e32 v93, v93, v94
	v_mul_f32_e32 v93, v99, v93
	global_store_dword v116, v93, s[16:17] offset:256
	v_mul_f32_e32 v93, v102, v53
	v_mul_f32_e32 v99, v37, v75
	v_mul_f32_e32 v94, 0x3f3504f3, v93
	v_cmp_nlt_f32_e64 s[20:21], |v94|, 1.0
	s_and_saveexec_b64 s[22:23], s[20:21]
	s_xor_b64 s[20:21], exec, s[22:23]
	s_cbranch_execz .Lpd_erf_a3
	v_fma_f32 v95, |v94|, s25, v91
	v_fma_f32 v95, |v94|, v95, s26
	v_fma_f32 v95, |v94|, v95, s27
	v_fma_f32 v95, |v94|, v95, s28
	v_fma_f32 v95, |v94|, v95, s29
	v_fma_f32 v95, |v94|, v95, s30
	v_fma_f32 v95, |v94|, v95, |v94|
	v_mul_f32_e32 v96, 0xbfb8aa3b, v95
	v_fma_f32 v97, v95, s31, -v96
	v_rndne_f32_e32 v98, v96
	v_fmac_f32_e32 v97, 0xb2a5705f, v95
	v_sub_f32_e32 v96, v96, v98
	v_add_f32_e32 v96, v96, v97
	v_cvt_i32_f32_e32 v97, v98
	v_exp_f32_e32 v96, v96
	v_cmp_nlt_f32_e32 vcc, s36, v95
	v_ldexp_f32 v96, v96, v97
	s_nop 0
	v_cndmask_b32_e32 v96, 0, v96, vcc
	v_cmp_ngt_f32_e32 vcc, s37, v95
	s_nop 1
	v_cndmask_b32_e32 v95, v92, v96, vcc
	v_sub_f32_e32 v95, 1.0, v95

; DI void phase_peer_down(const Params& p) {
;     ...
;         const float r1 = reduce8(part, lane) * sd;
;         const bool mine = (lane >> 3) == bi;
;         racc = mine ? r1 : racc; gacc = mine ? gsel * su : gacc;
;       }
;       const float act = 0.5f * racc * (1.f + erff(racc * 0.70710678118654752f));
;       coefw[slot] = gacc * act;
.Lpd_erf_b3:
	s_or_b64 exec, exec, s[20:21]
	v_bfi_b32 v94, s38, v95, v94
	v_mul_f32_e32 v93, 0.5, v93
	v_add_f32_e32 v94, 1.0, v94
	v_mul_f32_e32 v93, v93, v94
	v_mul_f32_e32 v93, v99, v93
	global_store_dword v117, v93, s[16:17]
	v_mul_f32_e32 v93, v103, v67
	v_mul_f32_e32 v99, v45, v83
	v_mul_f32_e32 v94, 0x3f3504f3, v93
	v_cmp_nlt_f32_e64 s[20:21], |v94|, 1.0
	s_and_saveexec_b64 s[22:23], s[20:21]
	s_xor_b64 s[20:21], exec, s[22:23]
	s_cbranch_execz .Lpd_erf_a4
	v_fma_f32 v95, |v94|, s25, v91
	v_fma_f32 v95, |v94|, v95, s26
	v_fma_f32 v95, |v94|, v95, s27
	v_fma_f32 v95, |v94|, v95, s28
	v_fma_f32 v95, |v94|, v95, s29
	v_fma_f32 v95, |v94|, v95, s30
	v_fma_f32 v95, |v94|, v95, |v94|
	v_mul_f32_e32 v96, 0xbfb8aa3b, v95
	v_fma_f32 v97, v95, s31, -v96
	v_rndne_f32_e32 v98, v96
	v_fmac_f32_e32 v97, 0xb2a5705f, v95
	v_sub_f32_e32 v96, v96, v98
	v_add_f32_e32 v96, v96, v97
	v_cvt_i32_f32_e32 v97, v98
	v_exp_f32_e32 v96, v96
	v_cmp_nlt_f32_e32 vcc, s36, v95
	v_ldexp_f32 v96, v96, v97
	s_nop 0
	v_cndmask_b32_e32 v96, 0, v96, vcc
	v_cmp_ngt_f32_e32 vcc, s37, v95
	s_nop 1
	v_cndmask_b32_e32 v95, v92, v96, vcc
	v_sub_f32_e32 v95, 1.0, v95

; DI void phase_peer_down(const Params& p) {
;     ...
;         const float r1 = reduce8(part, lane) * sd;
;         const bool mine = (lane >> 3) == bi;
;         racc = mine ? r1 : racc; gacc = mine ? gsel * su : gacc;
;       }
;       const float act = 0.5f * racc * (1.f + erff(racc * 0.70710678118654752f));
;       coefw[slot] = gacc * act;
.Lpd_erf_b4:
	s_or_b64 exec, exec, s[20:21]
	v_bfi_b32 v94, s38, v95, v94
	v_mul_f32_e32 v93, 0.5, v93
	v_add_f32_e32 v94, 1.0, v94
	v_mul_f32_e32 v93, v93, v94
	v_mul_f32_e32 v93, v99, v93
	global_store_dword v117, v93, s[16:17] offset:256
	v_mul_f32_e32 v93, v104, v54
	v_mul_f32_e32 v99, v38, v76
	v_mul_f32_e32 v94, 0x3f3504f3, v93
	v_cmp_nlt_f32_e64 s[20:21], |v94|, 1.0
	s_and_saveexec_b64 s[22:23], s[20:21]
	s_xor_b64 s[20:21], exec, s[22:23]
	s_cbranch_execz .Lpd_erf_a5
	v_fma_f32 v95, |v94|, s25, v91
	v_fma_f32 v95, |v94|, v95, s26
	v_fma_f32 v95, |v94|, v95, s27
	v_fma_f32 v95, |v94|, v95, s28
	v_fma_f32 v95, |v94|, v95, s29
	v_fma_f32 v95, |v94|, v95, s30
	v_fma_f32 v95, |v94|, v95, |v94|
	v_mul_f32_e32 v96, 0xbfb8aa3b, v95
	v_fma_f32 v97, v95, s31, -v96
	v_rndne_f32_e32 v98, v96
	v_fmac_f32_e32 v97, 0xb2a5705f, v95
	v_sub_f32_e32 v96, v96, v98
	v_add_f32_e32 v96, v96, v97
	v_cvt_i32_f32_e32 v97, v98
	v_exp_f32_e32 v96, v96
	v_cmp_nlt_f32_e32 vcc, s36, v95
	v_ldexp_f32 v96, v96, v97
	s_nop 0
	v_cndmask_b32_e32 v96, 0, v96, vcc
	v_cmp_ngt_f32_e32 vcc, s37, v95
	s_nop 1
	v_cndmask_b32_e32 v95, v92, v96, vcc
	v_sub_f32_e32 v95, 1.0, v95

; DI void phase_peer_down(const Params& p) {
;     ...
;         const float r1 = reduce8(part, lane) * sd;
;         const bool mine = (lane >> 3) == bi;
;         racc = mine ? r1 : racc; gacc = mine ? gsel * su : gacc;
;       }
;       const float act = 0.5f * racc * (1.f + erff(racc * 0.70710678118654752f));
;       coefw[slot] = gacc * act;
.Lpd_erf_b5:
	s_or_b64 exec, exec, s[20:21]
	v_bfi_b32 v94, s38, v95, v94
	v_mul_f32_e32 v93, 0.5, v93
	v_add_f32_e32 v94, 1.0, v94
	v_mul_f32_e32 v93, v93, v94
	v_mul_f32_e32 v93, v99, v93
	global_store_dword v118, v93, s[16:17]
	v_mul_f32_e32 v93, v105, v68
	v_mul_f32_e32 v99, v46, v84
	v_mul_f32_e32 v94, 0x3f3504f3, v93
	v_cmp_nlt_f32_e64 s[20:21], |v94|, 1.0
	s_and_saveexec_b64 s[22:23], s[20:21]
	s_xor_b64 s[20:21], exec, s[22:23]
	s_cbranch_execz .Lpd_erf_a6
	v_fma_f32 v95, |v94|, s25, v91
	v_fma_f32 v95, |v94|, v95, s26
	v_fma_f32 v95, |v94|, v95, s27
	v_fma_f32 v95, |v94|, v95, s28
	v_fma_f32 v95, |v94|, v95, s29
	v_fma_f32 v95, |v94|, v95, s30
	v_fma_f32 v95, |v94|, v95, |v94|
	v_mul_f32_e32 v96, 0xbfb8aa3b, v95
	v_fma_f32 v97, v95, s31, -v96
	v_rndne_f32_e32 v98, v96
	v_fmac_f32_e32 v97, 0xb2a5705f, v95
	v_sub_f32_e32 v96, v96, v98
	v_add_f32_e32 v96, v96, v97
	v_cvt_i32_f32_e32 v97, v98
	v_exp_f32_e32 v96, v96
	v_cmp_nlt_f32_e32 vcc, s36, v95
	v_ldexp_f32 v96, v96, v97
	s_nop 0
	v_cndmask_b32_e32 v96, 0, v96, vcc
	v_cmp_ngt_f32_e32 vcc, s37, v95
	s_nop 1
	v_cndmask_b32_e32 v95, v92, v96, vcc
	v_sub_f32_e32 v95, 1.0, v95

; DI void phase_peer_down(const Params& p) {
;     ...
;         const float r1 = reduce8(part, lane) * sd;
;         const bool mine = (lane >> 3) == bi;
;         racc = mine ? r1 : racc; gacc = mine ? gsel * su : gacc;
;       }
;       const float act = 0.5f * racc * (1.f + erff(racc * 0.70710678118654752f));
;       coefw[slot] = gacc * act;
.Lpd_erf_b6:
	s_or_b64 exec, exec, s[20:21]
	v_bfi_b32 v94, s38, v95, v94
	v_mul_f32_e32 v93, 0.5, v93
	v_add_f32_e32 v94, 1.0, v94
	v_mul_f32_e32 v93, v93, v94
	v_mul_f32_e32 v93, v99, v93
	global_store_dword v118, v93, s[16:17] offset:256
	v_mul_f32_e32 v93, v106, v55
	v_mul_f32_e32 v99, v39, v77
	v_mul_f32_e32 v94, 0x3f3504f3, v93
	v_cmp_nlt_f32_e64 s[20:21], |v94|, 1.0
	s_and_saveexec_b64 s[22:23], s[20:21]
	s_xor_b64 s[20:21], exec, s[22:23]
	s_cbranch_execz .Lpd_erf_a7
	v_fma_f32 v95, |v94|, s25, v91
	v_fma_f32 v95, |v94|, v95, s26
	v_fma_f32 v95, |v94|, v95, s27
	v_fma_f32 v95, |v94|, v95, s28
	v_fma_f32 v95, |v94|, v95, s29
	v_fma_f32 v95, |v94|, v95, s30
	v_fma_f32 v95, |v94|, v95, |v94|
	v_mul_f32_e32 v96, 0xbfb8aa3b, v95
	v_fma_f32 v97, v95, s31, -v96
	v_rndne_f32_e32 v98, v96
	v_fmac_f32_e32 v97, 0xb2a5705f, v95
	v_sub_f32_e32 v96, v96, v98
	v_add_f32_e32 v96, v96, v97
	v_cvt_i32_f32_e32 v97, v98
	v_exp_f32_e32 v96, v96
	v_cmp_nlt_f32_e32 vcc, s36, v95
	v_ldexp_f32 v96, v96, v97
	s_nop 0
	v_cndmask_b32_e32 v96, 0, v96, vcc
	v_cmp_ngt_f32_e32 vcc, s37, v95
	s_nop 1
	v_cndmask_b32_e32 v95, v92, v96, vcc
	v_sub_f32_e32 v95, 1.0, v95

; DI void phase_peer_down(const Params& p) {
;     ...
;         const float r1 = reduce8(part, lane) * sd;
;         const bool mine = (lane >> 3) == bi;
;         racc = mine ? r1 : racc; gacc = mine ? gsel * su : gacc;
;       }
;       const float act = 0.5f * racc * (1.f + erff(racc * 0.70710678118654752f));
;       coefw[slot] = gacc * act;
.Lpd_erf_b7:
	s_or_b64 exec, exec, s[20:21]
	v_bfi_b32 v94, s38, v95, v94
	v_mul_f32_e32 v93, 0.5, v93
	v_add_f32_e32 v94, 1.0, v94
	v_mul_f32_e32 v93, v93, v94
	v_mul_f32_e32 v93, v99, v93
	global_store_dword v119, v93, s[16:17]
	v_mul_f32_e32 v93, v107, v69
	v_mul_f32_e32 v99, v47, v85
	v_mul_f32_e32 v94, 0x3f3504f3, v93
	v_cmp_nlt_f32_e64 s[20:21], |v94|, 1.0
	s_and_saveexec_b64 s[22:23], s[20:21]
	s_xor_b64 s[20:21], exec, s[22:23]
	s_cbranch_execz .Lpd_erf_a8
	v_fma_f32 v95, |v94|, s25, v91
	v_fma_f32 v95, |v94|, v95, s26
	v_fma_f32 v95, |v94|, v95, s27
	v_fma_f32 v95, |v94|, v95, s28
	v_fma_f32 v95, |v94|, v95, s29
	v_fma_f32 v95, |v94|, v95, s30
	v_fma_f32 v95, |v94|, v95, |v94|
	v_mul_f32_e32 v96, 0xbfb8aa3b, v95
	v_fma_f32 v97, v95, s31, -v96
	v_rndne_f32_e32 v98, v96
	v_fmac_f32_e32 v97, 0xb2a5705f, v95
	v_sub_f32_e32 v96, v96, v98
	v_add_f32_e32 v96, v96, v97
	v_cvt_i32_f32_e32 v97, v98
	v_exp_f32_e32 v96, v96
	v_cmp_nlt_f32_e32 vcc, s36, v95
	v_ldexp_f32 v96, v96, v97
	s_nop 0
	v_cndmask_b32_e32 v96, 0, v96, vcc
	v_cmp_ngt_f32_e32 vcc, s37, v95
	s_nop 1
	v_cndmask_b32_e32 v95, v92, v96, vcc
	v_sub_f32_e32 v95, 1.0, v95

; DI void phase_peer_down(const Params& p) {
;     ...
;         const float r1 = reduce8(part, lane) * sd;
;         const bool mine = (lane >> 3) == bi;
;         racc = mine ? r1 : racc; gacc = mine ? gsel * su : gacc;
;       }
;       const float act = 0.5f * racc * (1.f + erff(racc * 0.70710678118654752f));
;       coefw[slot] = gacc * act;
.Lpd_erf_b8:
	s_or_b64 exec, exec, s[20:21]
	v_bfi_b32 v94, s38, v95, v94
	v_mul_f32_e32 v93, 0.5, v93
	v_add_f32_e32 v94, 1.0, v94
	v_mul_f32_e32 v93, v93, v94
	v_mul_f32_e32 v93, v99, v93
	global_store_dword v119, v93, s[16:17] offset:256
	v_mul_f32_e32 v93, v108, v56
	v_mul_f32_e32 v99, v40, v78
	v_mul_f32_e32 v94, 0x3f3504f3, v93
	v_cmp_nlt_f32_e64 s[20:21], |v94|, 1.0
	s_and_saveexec_b64 s[22:23], s[20:21]
	s_xor_b64 s[20:21], exec, s[22:23]
	s_cbranch_execz .Lpd_erf_a9
	v_fma_f32 v95, |v94|, s25, v91
	v_fma_f32 v95, |v94|, v95, s26
	v_fma_f32 v95, |v94|, v95, s27
	v_fma_f32 v95, |v94|, v95, s28
	v_fma_f32 v95, |v94|, v95, s29
	v_fma_f32 v95, |v94|, v95, s30
	v_fma_f32 v95, |v94|, v95, |v94|
	v_mul_f32_e32 v96, 0xbfb8aa3b, v95
	v_fma_f32 v97, v95, s31, -v96
	v_rndne_f32_e32 v98, v96
	v_fmac_f32_e32 v97, 0xb2a5705f, v95
	v_sub_f32_e32 v96, v96, v98
	v_add_f32_e32 v96, v96, v97
	v_cvt_i32_f32_e32 v97, v98
	v_exp_f32_e32 v96, v96
	v_cmp_nlt_f32_e32 vcc, s36, v95
	v_ldexp_f32 v96, v96, v97
	s_nop 0
	v_cndmask_b32_e32 v96, 0, v96, vcc
	v_cmp_ngt_f32_e32 vcc, s37, v95
	s_nop 1
	v_cndmask_b32_e32 v95, v92, v96, vcc
	v_sub_f32_e32 v95, 1.0, v95

; DI void phase_peer_down(const Params& p) {
;     ...
;         const float r1 = reduce8(part, lane) * sd;
;         const bool mine = (lane >> 3) == bi;
;         racc = mine ? r1 : racc; gacc = mine ? gsel * su : gacc;
;       }
;       const float act = 0.5f * racc * (1.f + erff(racc * 0.70710678118654752f));
;       coefw[slot] = gacc * act;
.Lpd_erf_b9:
	s_or_b64 exec, exec, s[20:21]
	v_bfi_b32 v94, s38, v95, v94
	v_mul_f32_e32 v93, 0.5, v93
	v_add_f32_e32 v94, 1.0, v94
	v_mul_f32_e32 v93, v93, v94
	v_mul_f32_e32 v93, v99, v93
	global_store_dword v120, v93, s[16:17]
	v_mul_f32_e32 v93, v109, v70
	v_mul_f32_e32 v99, v48, v86
	v_mul_f32_e32 v94, 0x3f3504f3, v93
	v_cmp_nlt_f32_e64 s[20:21], |v94|, 1.0
	s_and_saveexec_b64 s[22:23], s[20:21]
	s_xor_b64 s[20:21], exec, s[22:23]
	s_cbranch_execz .Lpd_erf_a10
	v_fma_f32 v95, |v94|, s25, v91
	v_fma_f32 v95, |v94|, v95, s26
	v_fma_f32 v95, |v94|, v95, s27
	v_fma_f32 v95, |v94|, v95, s28
	v_fma_f32 v95, |v94|, v95, s29
	v_fma_f32 v95, |v94|, v95, s30
	v_fma_f32 v95, |v94|, v95, |v94|
	v_mul_f32_e32 v96, 0xbfb8aa3b, v95
	v_fma_f32 v97, v95, s31, -v96
	v_rndne_f32_e32 v98, v96
	v_fmac_f32_e32 v97, 0xb2a5705f, v95
	v_sub_f32_e32 v96, v96, v98
	v_add_f32_e32 v96, v96, v97
	v_cvt_i32_f32_e32 v97, v98
	v_exp_f32_e32 v96, v96
	v_cmp_nlt_f32_e32 vcc, s36, v95
	v_ldexp_f32 v96, v96, v97
	s_nop 0
	v_cndmask_b32_e32 v96, 0, v96, vcc
	v_cmp_ngt_f32_e32 vcc, s37, v95
	s_nop 1
	v_cndmask_b32_e32 v95, v92, v96, vcc
	v_sub_f32_e32 v95, 1.0, v95

; DI void phase_peer_down(const Params& p) {
;     ...
;         const float r1 = reduce8(part, lane) * sd;
;         const bool mine = (lane >> 3) == bi;
;         racc = mine ? r1 : racc; gacc = mine ? gsel * su : gacc;
;       }
;       const float act = 0.5f * racc * (1.f + erff(racc * 0.70710678118654752f));
;       coefw[slot] = gacc * act;
.Lpd_erf_b10:
	s_or_b64 exec, exec, s[20:21]
	v_bfi_b32 v94, s38, v95, v94
	v_mul_f32_e32 v93, 0.5, v93
	v_add_f32_e32 v94, 1.0, v94
	v_mul_f32_e32 v93, v93, v94
	v_mul_f32_e32 v93, v99, v93
	global_store_dword v120, v93, s[16:17] offset:256
	v_mul_f32_e32 v93, v110, v57
	v_mul_f32_e32 v99, v41, v79
	v_mul_f32_e32 v94, 0x3f3504f3, v93
	v_cmp_nlt_f32_e64 s[20:21], |v94|, 1.0
	s_and_saveexec_b64 s[22:23], s[20:21]
	s_xor_b64 s[20:21], exec, s[22:23]
	s_cbranch_execz .Lpd_erf_a11
	v_fma_f32 v95, |v94|, s25, v91
	v_fma_f32 v95, |v94|, v95, s26
	v_fma_f32 v95, |v94|, v95, s27
	v_fma_f32 v95, |v94|, v95, s28
	v_fma_f32 v95, |v94|, v95, s29
	v_fma_f32 v95, |v94|, v95, s30
	v_fma_f32 v95, |v94|, v95, |v94|
	v_mul_f32_e32 v96, 0xbfb8aa3b, v95
	v_fma_f32 v97, v95, s31, -v96
	v_rndne_f32_e32 v98, v96
	v_fmac_f32_e32 v97, 0xb2a5705f, v95
	v_sub_f32_e32 v96, v96, v98
	v_add_f32_e32 v96, v96, v97
	v_cvt_i32_f32_e32 v97, v98
	v_exp_f32_e32 v96, v96
	v_cmp_nlt_f32_e32 vcc, s36, v95
	v_ldexp_f32 v96, v96, v97
	s_nop 0
	v_cndmask_b32_e32 v96, 0, v96, vcc
	v_cmp_ngt_f32_e32 vcc, s37, v95
	s_nop 1
	v_cndmask_b32_e32 v95, v92, v96, vcc
	v_sub_f32_e32 v95, 1.0, v95

; DI void phase_peer_down(const Params& p) {
;     ...
;         const float r1 = reduce8(part, lane) * sd;
;         const bool mine = (lane >> 3) == bi;
;         racc = mine ? r1 : racc; gacc = mine ? gsel * su : gacc;
;       }
;       const float act = 0.5f * racc * (1.f + erff(racc * 0.70710678118654752f));
;       coefw[slot] = gacc * act;
.Lpd_erf_b11:
	s_or_b64 exec, exec, s[20:21]
	v_bfi_b32 v94, s38, v95, v94
	v_mul_f32_e32 v93, 0.5, v93
	v_add_f32_e32 v94, 1.0, v94
	v_mul_f32_e32 v93, v93, v94
	v_mul_f32_e32 v93, v99, v93
	global_store_dword v121, v93, s[16:17]
	v_mul_f32_e32 v93, v111, v71
	v_mul_f32_e32 v99, v49, v87
	v_mul_f32_e32 v94, 0x3f3504f3, v93
	v_cmp_nlt_f32_e64 s[20:21], |v94|, 1.0
	s_and_saveexec_b64 s[22:23], s[20:21]
	s_xor_b64 s[20:21], exec, s[22:23]
	s_cbranch_execz .Lpd_erf_a12
	v_fma_f32 v95, |v94|, s25, v91
	v_fma_f32 v95, |v94|, v95, s26
	v_fma_f32 v95, |v94|, v95, s27
	v_fma_f32 v95, |v94|, v95, s28
	v_fma_f32 v95, |v94|, v95, s29
	v_fma_f32 v95, |v94|, v95, s30
	v_fma_f32 v95, |v94|, v95, |v94|
	v_mul_f32_e32 v96, 0xbfb8aa3b, v95
	v_fma_f32 v97, v95, s31, -v96
	v_rndne_f32_e32 v98, v96
	v_fmac_f32_e32 v97, 0xb2a5705f, v95
	v_sub_f32_e32 v96, v96, v98
	v_add_f32_e32 v96, v96, v97
	v_cvt_i32_f32_e32 v97, v98
	v_exp_f32_e32 v96, v96
	v_cmp_nlt_f32_e32 vcc, s36, v95
	v_ldexp_f32 v96, v96, v97
	s_nop 0
	v_cndmask_b32_e32 v96, 0, v96, vcc
	v_cmp_ngt_f32_e32 vcc, s37, v95
	s_nop 1
	v_cndmask_b32_e32 v95, v92, v96, vcc
	v_sub_f32_e32 v95, 1.0, v95

; DI void phase_peer_down(const Params& p) {
;     ...
;         const float r1 = reduce8(part, lane) * sd;
;         const bool mine = (lane >> 3) == bi;
;         racc = mine ? r1 : racc; gacc = mine ? gsel * su : gacc;
;       }
;       const float act = 0.5f * racc * (1.f + erff(racc * 0.70710678118654752f));
;       coefw[slot] = gacc * act;
.Lpd_erf_b12:
	s_or_b64 exec, exec, s[20:21]
	v_bfi_b32 v94, s38, v95, v94
	v_mul_f32_e32 v93, 0.5, v93
	v_add_f32_e32 v94, 1.0, v94
	v_mul_f32_e32 v93, v93, v94
	v_mul_f32_e32 v93, v99, v93
	global_store_dword v121, v93, s[16:17] offset:256
	v_mul_f32_e32 v93, v112, v58
	v_mul_f32_e32 v99, v42, v80
	v_mul_f32_e32 v94, 0x3f3504f3, v93
	v_cmp_nlt_f32_e64 s[20:21], |v94|, 1.0
	s_and_saveexec_b64 s[22:23], s[20:21]
	s_xor_b64 s[20:21], exec, s[22:23]
	s_cbranch_execz .Lpd_erf_a13
	v_fma_f32 v95, |v94|, s25, v91
	v_fma_f32 v95, |v94|, v95, s26
	v_fma_f32 v95, |v94|, v95, s27
	v_fma_f32 v95, |v94|, v95, s28
	v_fma_f32 v95, |v94|, v95, s29
	v_fma_f32 v95, |v94|, v95, s30
	v_fma_f32 v95, |v94|, v95, |v94|
	v_mul_f32_e32 v96, 0xbfb8aa3b, v95
	v_fma_f32 v97, v95, s31, -v96
	v_rndne_f32_e32 v98, v96
	v_fmac_f32_e32 v97, 0xb2a5705f, v95
	v_sub_f32_e32 v96, v96, v98
	v_add_f32_e32 v96, v96, v97
	v_cvt_i32_f32_e32 v97, v98
	v_exp_f32_e32 v96, v96
	v_cmp_nlt_f32_e32 vcc, s36, v95
	v_ldexp_f32 v96, v96, v97
	s_nop 0
	v_cndmask_b32_e32 v96, 0, v96, vcc
	v_cmp_ngt_f32_e32 vcc, s37, v95
	s_nop 1
	v_cndmask_b32_e32 v95, v92, v96, vcc
	v_sub_f32_e32 v95, 1.0, v95

; DI void phase_peer_down(const Params& p) {
;     ...
;         const float r1 = reduce8(part, lane) * sd;
;         const bool mine = (lane >> 3) == bi;
;         racc = mine ? r1 : racc; gacc = mine ? gsel * su : gacc;
;       }
;       const float act = 0.5f * racc * (1.f + erff(racc * 0.70710678118654752f));
;       coefw[slot] = gacc * act;
.Lpd_erf_b13:
	s_or_b64 exec, exec, s[20:21]
	v_bfi_b32 v94, s38, v95, v94
	v_mul_f32_e32 v93, 0.5, v93
	v_add_f32_e32 v94, 1.0, v94
	v_mul_f32_e32 v93, v93, v94
	v_mul_f32_e32 v93, v99, v93
	global_store_dword v122, v93, s[16:17]
	v_mul_f32_e32 v93, v113, v72
	v_mul_f32_e32 v99, v50, v88
	v_mul_f32_e32 v94, 0x3f3504f3, v93
	v_cmp_nlt_f32_e64 s[20:21], |v94|, 1.0
	s_and_saveexec_b64 s[22:23], s[20:21]
	s_xor_b64 s[20:21], exec, s[22:23]
	s_cbranch_execz .Lpd_erf_a14
	v_fma_f32 v95, |v94|, s25, v91
	v_fma_f32 v95, |v94|, v95, s26
	v_fma_f32 v95, |v94|, v95, s27
	v_fma_f32 v95, |v94|, v95, s28
	v_fma_f32 v95, |v94|, v95, s29
	v_fma_f32 v95, |v94|, v95, s30
	v_fma_f32 v95, |v94|, v95, |v94|
	v_mul_f32_e32 v96, 0xbfb8aa3b, v95
	v_fma_f32 v97, v95, s31, -v96
	v_rndne_f32_e32 v98, v96
	v_fmac_f32_e32 v97, 0xb2a5705f, v95
	v_sub_f32_e32 v96, v96, v98
	v_add_f32_e32 v96, v96, v97
	v_cvt_i32_f32_e32 v97, v98
	v_exp_f32_e32 v96, v96
	v_cmp_nlt_f32_e32 vcc, s36, v95
	v_ldexp_f32 v96, v96, v97
	s_nop 0
	v_cndmask_b32_e32 v96, 0, v96, vcc
	v_cmp_ngt_f32_e32 vcc, s37, v95
	s_nop 1
	v_cndmask_b32_e32 v95, v92, v96, vcc
	v_sub_f32_e32 v95, 1.0, v95

; DI void phase_peer_down(const Params& p) {
;     ...
;         const float r1 = reduce8(part, lane) * sd;
;         const bool mine = (lane >> 3) == bi;
;         racc = mine ? r1 : racc; gacc = mine ? gsel * su : gacc;
;       }
;       const float act = 0.5f * racc * (1.f + erff(racc * 0.70710678118654752f));
;       coefw[slot] = gacc * act;
.Lpd_erf_b14:
	s_or_b64 exec, exec, s[20:21]
	v_bfi_b32 v94, s38, v95, v94
	v_mul_f32_e32 v93, 0.5, v93
	v_add_f32_e32 v94, 1.0, v94
	v_mul_f32_e32 v93, v93, v94
	v_mul_f32_e32 v93, v99, v93
	global_store_dword v122, v93, s[16:17] offset:256
	v_mul_f32_e32 v93, v114, v59
	v_mul_f32_e32 v99, v43, v81
	v_mul_f32_e32 v94, 0x3f3504f3, v93
	v_cmp_nlt_f32_e64 s[20:21], |v94|, 1.0
	s_and_saveexec_b64 s[22:23], s[20:21]
	s_xor_b64 s[20:21], exec, s[22:23]
	s_cbranch_execz .Lpd_erf_a15
	v_fma_f32 v95, |v94|, s25, v91
	v_fma_f32 v95, |v94|, v95, s26
	v_fma_f32 v95, |v94|, v95, s27
	v_fma_f32 v95, |v94|, v95, s28
	v_fma_f32 v95, |v94|, v95, s29
	v_fma_f32 v95, |v94|, v95, s30
	v_fma_f32 v95, |v94|, v95, |v94|
	v_mul_f32_e32 v96, 0xbfb8aa3b, v95
	v_fma_f32 v97, v95, s31, -v96
	v_rndne_f32_e32 v98, v96
	v_fmac_f32_e32 v97, 0xb2a5705f, v95
	v_sub_f32_e32 v96, v96, v98
	v_add_f32_e32 v96, v96, v97
	v_cvt_i32_f32_e32 v97, v98
	v_exp_f32_e32 v96, v96
	v_cmp_nlt_f32_e32 vcc, s36, v95
	v_ldexp_f32 v96, v96, v97
	s_nop 0
	v_cndmask_b32_e32 v96, 0, v96, vcc
	v_cmp_ngt_f32_e32 vcc, s37, v95
	s_nop 1
	v_cndmask_b32_e32 v95, v92, v96, vcc
	v_sub_f32_e32 v95, 1.0, v95

; DI void phase_peer_down(const Params& p) {
;     ...
;         const float r1 = reduce8(part, lane) * sd;
;         const bool mine = (lane >> 3) == bi;
;         racc = mine ? r1 : racc; gacc = mine ? gsel * su : gacc;
;       }
;       const float act = 0.5f * racc * (1.f + erff(racc * 0.70710678118654752f));
;       coefw[slot] = gacc * act;
.Lpd_erf_b15:
	s_or_b64 exec, exec, s[20:21]
	v_bfi_b32 v94, s38, v95, v94
	v_mul_f32_e32 v93, 0.5, v93
	v_add_f32_e32 v94, 1.0, v94
	v_mul_f32_e32 v93, v93, v94
	v_mul_f32_e32 v93, v99, v93
	global_store_dword v123, v93, s[16:17]
	v_mul_f32_e32 v93, v115, v73
	v_mul_f32_e32 v99, v51, v89
	v_mul_f32_e32 v94, 0x3f3504f3, v93
	v_cmp_nlt_f32_e64 s[20:21], |v94|, 1.0
	s_and_saveexec_b64 s[22:23], s[20:21]
	s_xor_b64 s[20:21], exec, s[22:23]
	s_cbranch_execz .Lpd_erf_a16
	v_fma_f32 v95, |v94|, s25, v91
	v_fma_f32 v95, |v94|, v95, s26
	v_fma_f32 v95, |v94|, v95, s27
	v_fma_f32 v95, |v94|, v95, s28
	v_fma_f32 v95, |v94|, v95, s29
	v_fma_f32 v95, |v94|, v95, s30
	v_fma_f32 v95, |v94|, v95, |v94|
	v_mul_f32_e32 v96, 0xbfb8aa3b, v95
	v_fma_f32 v97, v95, s31, -v96
	v_rndne_f32_e32 v98, v96
	v_fmac_f32_e32 v97, 0xb2a5705f, v95
	v_sub_f32_e32 v96, v96, v98
	v_add_f32_e32 v96, v96, v97
	v_cvt_i32_f32_e32 v97, v98
	v_exp_f32_e32 v96, v96
	v_cmp_nlt_f32_e32 vcc, s36, v95
	v_ldexp_f32 v96, v96, v97
	s_nop 0
	v_cndmask_b32_e32 v96, 0, v96, vcc
	v_cmp_ngt_f32_e32 vcc, s37, v95
	s_nop 1
	v_cndmask_b32_e32 v95, v92, v96, vcc
	v_sub_f32_e32 v95, 1.0, v95

; DI void phase_peer_down(const Params& p) {
;     ...
;         const float r1 = reduce8(part, lane) * sd;
;         const bool mine = (lane >> 3) == bi;
;         racc = mine ? r1 : racc; gacc = mine ? gsel * su : gacc;
;       }
;       const float act = 0.5f * racc * (1.f + erff(racc * 0.70710678118654752f));
;       coefw[slot] = gacc * act;
.Lpd_erf_b16:
	s_or_b64 exec, exec, s[20:21]
	v_bfi_b32 v94, s38, v95, v94
	v_mul_f32_e32 v93, 0.5, v93
	v_add_f32_e32 v94, 1.0, v94
	v_mul_f32_e32 v93, v93, v94
	v_mul_f32_e32 v93, v99, v93
	global_store_dword v123, v93, s[16:17] offset:256
	s_add_i32 s18, s18, 8
	s_cmpk_lt_u32 s18, 16
	s_cbranch_scc1 .Lpd_epi
